# in-proj GEMM K-loops: one dword per A row touched 2 K-steps ahead to pre-warm L2 for the LDS-DMA
# baseline (speedup 1.0000x reference)
; __device__ __forceinline__ int otid() { int t = threadIdx.x; asm volatile("" : "+v"(t)); return t; }
; template <int MI, bool SWAP, bool F8 = false>
; __device__ __forceinline__ void gemm_core(const bf16_t* __restrict__ A, int lda, const bf16_t* __restrict__ B, int ldb,
;                                           int K, char* smem, f32x4 (&acc)[MI][4]) {
;   const int tid = otid(), lane = tid & 63, w = tid >> 6, wm = w >> 1, wn = w & 1;
;   const int lr = tid >> 3, lc = tid & 7;
;   const int li = lane & 15, g = lane >> 4;
;   u32x4 ra[MI], rb[4];
;   const bf16_t* ap = A + (size_t)lr * lda + lc * 8;
;   const bf16_t* bp = B + (size_t)lr * ldb + lc * 8;
; #pragma unroll
;   for (int i = 0; i < MI; ++i)
; #pragma unroll
;     for (int j = 0; j < 4; ++j) acc[i][j] = (f32x4){0.f, 0.f, 0.f, 0.f};
;   const int nk = K >> 6;
; #pragma unroll
;   for (int i = 0; i < MI; ++i) ra[i] = *(const u32x4*)(ap + (size_t)(32 * i) * lda);
; #pragma unroll
;   for (int i = 0; i < 4; ++i) rb[i] = *(const u32x4*)(bp + (size_t)(32 * i) * ldb);
;   const int woff = lr * 128 + ((lc ^ (lr & 7)) << 4);
;   const int xrow = (wm * 16 * MI + li) * 128;
;   const int wrow = 32768 + (wn * 32 + li) * 128;
; __global__ void __launch_bounds__(256, 2) fwd_kernel(P p) {
;     ...
;       for (int it = blockIdx.x; it < 64 * 24; it += G) {
;         const int tm = (it & 7) * 8 + (it >> 3) / 24, tn = (it >> 3) % 24;
;         gemm_tile_bf16<8>(XN + (size_t)tm * 256 * 1024, 1024,
;                        (const bf16_t*)(ws + OFF_WOIN) + ((size_t)li2 * 3072 + tn * 128) * 1024, 1024, 1024,
;                        PR + (size_t)tm * 256 * 3072 + tn * 128, 3072, smem);
.LBB0_119:
	s_ashr_i32 s11, s28, 3
	s_mul_hi_i32 s20, s11, 0x2aaaaaab
	s_lshl_b32 s10, s28, 3
	s_lshr_b32 s21, s20, 31
	s_ashr_i32 s20, s20, 2
	s_and_b32 s10, s10, 56
	s_add_i32 s34, s20, s21
	s_add_i32 s10, s10, s34
	s_mul_i32 s20, s34, 24
	s_sub_i32 s30, s11, s20
	s_ashr_i32 s11, s10, 31
	s_waitcnt vmcnt(17)
	v_mov_b32_e32 v30, v208
	s_and_b32 s29, s27, 56
	s_lshl_b64 s[20:21], s[10:11], 19
	s_add_u32 s22, s19, s20
	v_ashrrev_i32_e32 v2, 3, v30
	v_ashrrev_i32_e32 v3, 31, v2
	s_addc_u32 s23, s24, s21
	v_lshlrev_b64 v[20:21], 11, v[2:3]
	v_lshlrev_b32_e32 v0, 4, v30
	v_lshl_add_u64 v[24:25], s[22:23], 0, v[20:21]
	v_and_b32_e32 v0, 0x70, v0
	v_lshl_add_u64 v[24:25], v[24:25], 0, v[0:1]
	v_add_co_u32_e32 v26, vcc, s93, v24
	s_lshl_b32 s20, s30, 7
	s_nop 0
	v_addc_co_u32_e32 v27, vcc, 0, v25, vcc
	v_lshrrev_b32_e32 v254, 3, v208
	v_and_b32_e32 v254, 7, v254
	v_xor_b32_e32 v252, v254, v208
	v_and_b32_e32 v252, 7, v252
	v_lshlrev_b32_e32 v252, 4, v252
	v_lshl_or_b32 v252, v254, 11, v252
	v_add_u32_e32 v253, 0x10000, v252
	v_lshrrev_b32_e32 v254, 6, v208
	s_nop 0
	v_readfirstlane_b32 s62, v254
	s_lshl_b32 s62, s62, 10
	v_readfirstlane_b32 s56, v24
	v_readfirstlane_b32 s57, v25
	v_lshrrev_b32_e32 v222, 6, v208
	v_and_b32_e32 v223, 63, v208
	v_mul_u32_u24_e32 v222, 56, v222
	v_add_u32_e32 v222, v222, v223
	v_lshlrev_b32_e32 v222, 11, v222
	v_add_co_u32_e32 v26, vcc, s46, v24
	s_ashr_i32 s21, s20, 31
	s_nop 0
	v_addc_co_u32_e32 v27, vcc, 0, v25, vcc
	v_add_co_u32_e32 v28, vcc, s47, v24
	s_mul_i32 s11, s18, 0xc00
	s_nop 0
	v_addc_co_u32_e32 v29, vcc, 0, v25, vcc
	v_add_co_u32_e32 v26, vcc, s50, v24
	s_add_u32 s30, s20, s11
	s_nop 0
	v_addc_co_u32_e32 v27, vcc, 0, v25, vcc
	s_addc_u32 s31, s21, 0
	v_add_co_u32_e32 v28, vcc, s51, v24
	s_lshl_b64 s[30:31], s[30:31], 11
	s_nop 0
	v_addc_co_u32_e32 v29, vcc, 0, v25, vcc
	s_mov_b32 s11, 0x60000
	s_add_u32 s30, s25, s30
	v_add_co_u32_e32 v26, vcc, s11, v24
	s_addc_u32 s31, s26, s31
	s_nop 0
	v_addc_co_u32_e32 v27, vcc, 0, v25, vcc
	s_mov_b32 s11, 0x70000
	v_lshl_add_u64 v[22:23], s[30:31], 0, v[20:21]
	v_add_co_u32_e32 v24, vcc, s11, v24
	v_lshl_add_u64 v[22:23], v[22:23], 0, v[0:1]
	s_nop 0
	v_addc_co_u32_e32 v25, vcc, 0, v25, vcc
	v_add_co_u32_e32 v24, vcc, s93, v22
	v_and_b32_e32 v3, 15, v30
	s_nop 0
	v_addc_co_u32_e32 v25, vcc, 0, v23, vcc
	s_nop 0
	v_readfirstlane_b32 s58, v22
	v_readfirstlane_b32 s59, v23
	v_add_co_u32_e32 v24, vcc, s46, v22
	s_add_i32 s22, s34, s29
	s_nop 0
	v_addc_co_u32_e32 v25, vcc, 0, v23, vcc
	v_add_co_u32_e32 v22, vcc, s47, v22
	v_lshrrev_b32_e32 v31, 4, v30
	s_nop 0
	v_addc_co_u32_e32 v23, vcc, 0, v23, vcc
	v_lshlrev_b32_e32 v22, 7, v2
	v_xor_b32_e32 v2, v2, v30
	v_lshlrev_b32_e32 v2, 4, v2
	v_and_or_b32 v207, v2, s33, v22
	v_lshlrev_b32_e32 v2, 7, v30
	v_and_b32_e32 v22, 0xffffc780, v2
	v_lshrrev_b32_e32 v2, 1, v30
	v_and_or_b32 v2, v2, 32, v3
	v_and_b32_e32 v24, 7, v30
	s_ashr_i32 s23, s22, 31
	v_lshlrev_b32_e32 v23, 7, v2
	v_bitop3_b32 v2, v31, v24, 3 bitop3:0x6c
	s_lshl_b64 s[22:23], s[22:23], 19
	v_bfe_u32 v0, v30, 4, 2
	v_lshlrev_b32_e32 v25, 4, v2
	v_lshl_add_u64 v[2:3], s[22:23], 0, v[20:21]
	s_lshl_b64 s[22:23], s[20:21], 11
	v_bitop3_b32 v0, v0, v24, 4 bitop3:0x36
	v_lshlrev_b32_e32 v24, 4, v24
	v_lshl_add_u64 v[20:21], v[20:21], 0, s[22:23]
	v_lshlrev_b32_e32 v0, 4, v0
	v_or_b32_e32 v2, v2, v24
	v_or_b32_e32 v20, v20, v24
	v_mov_b32_e32 v144, 0
	v_lshl_add_u64 v[2:3], s[12:13], 0, v[2:3]
	v_lshl_add_u64 v[204:205], s[6:7], 0, v[20:21]
	s_mov_b64 s[22:23], 0
	v_add_u32_e32 v215, v23, v25
	v_add_u32_e32 v213, v22, v25
	v_add_u32_e32 v206, v23, v0
	v_add_u32_e32 v0, v22, v0
	v_mov_b32_e32 v145, v144
	v_mov_b32_e32 v146, v144
	v_mov_b32_e32 v147, v144
	s_waitcnt vmcnt(26)
	v_mov_b32_e32 v92, v144
	v_mov_b32_e32 v93, v144
	v_mov_b32_e32 v94, v144
	v_mov_b32_e32 v95, v144
	s_waitcnt vmcnt(25)
	v_mov_b32_e32 v96, v144
	v_mov_b32_e32 v97, v144
	v_mov_b32_e32 v98, v144
	v_mov_b32_e32 v99, v144
	s_waitcnt vmcnt(24)
	v_mov_b32_e32 v100, v144
	v_mov_b32_e32 v101, v144
	v_mov_b32_e32 v102, v144
	v_mov_b32_e32 v103, v144
	v_mov_b32_e32 v108, v144
	v_mov_b32_e32 v109, v144
	v_mov_b32_e32 v110, v144
	v_mov_b32_e32 v111, v144
	v_mov_b32_e32 v112, v144
	v_mov_b32_e32 v113, v144
	v_mov_b32_e32 v114, v144
	v_mov_b32_e32 v115, v144
	s_waitcnt vmcnt(23)
	v_mov_b32_e32 v56, v144
	v_mov_b32_e32 v57, v144
	v_mov_b32_e32 v58, v144
	v_mov_b32_e32 v59, v144
	v_mov_b32_e32 v48, v144
	v_mov_b32_e32 v49, v144
	v_mov_b32_e32 v50, v144
	v_mov_b32_e32 v51, v144
	v_mov_b32_e32 v52, v144
	v_mov_b32_e32 v53, v144
	v_mov_b32_e32 v54, v144
	v_mov_b32_e32 v55, v144
	v_mov_b32_e32 v20, v144
	v_mov_b32_e32 v21, v144
	v_mov_b32_e32 v22, v144
	v_mov_b32_e32 v23, v144
	v_mov_b32_e32 v24, v144
	v_mov_b32_e32 v25, v144
	v_mov_b32_e32 v26, v144
	v_mov_b32_e32 v27, v144
	v_mov_b32_e32 v28, v144
	v_mov_b32_e32 v29, v144
	v_mov_b32_e32 v30, v144
	v_mov_b32_e32 v31, v144
	v_mov_b32_e32 v32, v144
	v_mov_b32_e32 v33, v144
	v_mov_b32_e32 v34, v144
	v_mov_b32_e32 v35, v144
	v_mov_b32_e32 v36, v144
	v_mov_b32_e32 v37, v144
	v_mov_b32_e32 v38, v144
	v_mov_b32_e32 v39, v144
	v_mov_b32_e32 v40, v144
	v_mov_b32_e32 v41, v144
	v_mov_b32_e32 v42, v144
	v_mov_b32_e32 v43, v144
	v_mov_b32_e32 v44, v144
	v_mov_b32_e32 v45, v144
	v_mov_b32_e32 v46, v144
	v_mov_b32_e32 v47, v144
	v_mov_b32_e32 v60, v144
	v_mov_b32_e32 v61, v144
	v_mov_b32_e32 v62, v144
	v_mov_b32_e32 v63, v144
	s_waitcnt vmcnt(22)
	v_mov_b32_e32 v64, v144
	v_mov_b32_e32 v65, v144
	v_mov_b32_e32 v66, v144
	v_mov_b32_e32 v67, v144
	v_mov_b32_e32 v68, v144
	v_mov_b32_e32 v69, v144
	v_mov_b32_e32 v70, v144
	v_mov_b32_e32 v71, v144
	v_mov_b32_e32 v72, v144
	v_mov_b32_e32 v73, v144
	v_mov_b32_e32 v74, v144
	v_mov_b32_e32 v75, v144
	v_mov_b32_e32 v76, v144
	v_mov_b32_e32 v77, v144
	v_mov_b32_e32 v78, v144
	v_mov_b32_e32 v79, v144
	v_mov_b32_e32 v80, v144
	v_mov_b32_e32 v81, v144
	v_mov_b32_e32 v82, v144
	v_mov_b32_e32 v83, v144
	s_waitcnt vmcnt(21)
	v_mov_b32_e32 v84, v144
	v_mov_b32_e32 v85, v144
	v_mov_b32_e32 v86, v144
	v_mov_b32_e32 v87, v144
	s_waitcnt vmcnt(20)
	v_mov_b32_e32 v88, v144
	v_mov_b32_e32 v89, v144
	v_mov_b32_e32 v90, v144
	v_mov_b32_e32 v91, v144
	v_mov_b32_e32 v104, v144
	v_mov_b32_e32 v105, v144
	v_mov_b32_e32 v106, v144
	v_mov_b32_e32 v107, v144
	v_mov_b32_e32 v116, v144
	v_mov_b32_e32 v117, v144
	v_mov_b32_e32 v118, v144
	v_mov_b32_e32 v119, v144
	v_mov_b32_e32 v120, v144
	v_mov_b32_e32 v121, v144
	v_mov_b32_e32 v122, v144
	v_mov_b32_e32 v123, v144
	v_mov_b32_e32 v124, v144
	v_mov_b32_e32 v125, v144
	v_mov_b32_e32 v126, v144
	v_mov_b32_e32 v127, v144
	v_mov_b32_e32 v128, v144
	v_mov_b32_e32 v129, v144
	v_mov_b32_e32 v130, v144
	v_mov_b32_e32 v131, v144
	v_mov_b32_e32 v132, v144
	v_mov_b32_e32 v133, v144
	v_mov_b32_e32 v134, v144
	v_mov_b32_e32 v135, v144
	v_mov_b32_e32 v136, v144
	v_mov_b32_e32 v137, v144
	v_mov_b32_e32 v138, v144
	v_mov_b32_e32 v139, v144
	v_mov_b32_e32 v140, v144
	v_mov_b32_e32 v141, v144
	v_mov_b32_e32 v142, v144
	v_mov_b32_e32 v143, v144
; template <int MI, bool SWAP, bool F8 = false>
; __device__ __forceinline__ void gemm_core(const bf16_t* __restrict__ A, int lda, const bf16_t* __restrict__ B, int ldb,
;                                           int K, char* smem, f32x4 (&acc)[MI][4]) {
;     ...
;   for (int kt = 0; kt < nk; ++kt) {
;     __syncthreads();
; #pragma unroll
;     for (int i = 0; i < MI; ++i) *(u32x4*)(smem + woff + i * 4096) = ra[i];
; #pragma unroll
;     for (int i = 0; i < 4; ++i) *(u32x4*)(smem + 32768 + woff + i * 4096) = rb[i];
;     __syncthreads();
;     if (kt + 1 < nk) {
; #pragma unroll
;       for (int i = 0; i < MI; ++i) ra[i] = *(const u32x4*)(ap + (size_t)(32 * i) * lda + (kt + 1) * 64);
; #pragma unroll
;       for (int i = 0; i < 4; ++i) rb[i] = *(const u32x4*)(bp + (size_t)(32 * i) * ldb + (kt + 1) * 64);
;     }
;     if (F8) {
;       const int c0 = (g ^ (li & 7)) << 4, c1 = ((4 + g) ^ (li & 7)) << 4;
;       i32x8 wf8[4];
; #pragma unroll
;       for (int j = 0; j < 4; ++j) {
;         const char* rp = smem + wrow + ((j & 1) * 16 + (j >> 1) * 64) * 128;
;         const u32x4 lo = *(const u32x4*)(rp + c0), hi = *(const u32x4*)(rp + c1);
;         wf8[j] = (i32x8){(int)lo.x, (int)lo.y, (int)lo.z, (int)lo.w, (int)hi.x, (int)hi.y, (int)hi.z, (int)hi.w};
;       }
; #pragma unroll
;       for (int i = 0; i < MI; ++i) {
;         const char* rp = smem + xrow + i * 2048;
;         const u32x4 lo = *(const u32x4*)(rp + c0), hi = *(const u32x4*)(rp + c1);
;         const i32x8 xf8 = {(int)lo.x, (int)lo.y, (int)lo.z, (int)lo.w, (int)hi.x, (int)hi.y, (int)hi.z, (int)hi.w};
; #pragma unroll
;         for (int j = 0; j < 4; ++j)
;           acc[i][j] = __builtin_amdgcn_mfma_scale_f32_16x16x128_f8f6f4(wf8[j], xf8, acc[i][j], 0, 0, 0, 0x77777777, 0, 0x7f7f7f7f);
;       }
;     } else {
; #pragma unroll
;     for (int kk = 0; kk < 2; ++kk) {
;       const int ch = ((kk * 4 + g) ^ (li & 7)) << 4;
;       bf16x8 xf[MI], wf[4];
; #pragma unroll
;       for (int j = 0; j < 4; ++j) wf[j] = *(const bf16x8*)(smem + wrow + ((j & 1) * 16 + (j >> 1) * 64) * 128 + ch);
; #pragma unroll
;       for (int i = 0; i < MI; ++i) xf[i] = *(const bf16x8*)(smem + xrow + i * 2048 + ch);
; #pragma unroll
;       for (int i = 0; i < MI; ++i)
; #pragma unroll
;         for (int j = 0; j < 4; ++j) {
.LBB0_120:
	s_barrier
	s_mov_b32 m0, s62
	s_nop 0
	global_load_lds_dwordx4 v252, s[56:57]
	s_add_u32 m0, s62, 0x1000
	s_nop 0
	global_load_lds_dwordx4 v253, s[56:57]
	s_add_u32 s56, s56, 0x20000
	s_addc_u32 s57, s57, 0
	s_add_u32 m0, s62, 0x2000
	s_nop 0
	global_load_lds_dwordx4 v252, s[56:57]
	s_add_u32 m0, s62, 0x3000
	s_nop 0
	global_load_lds_dwordx4 v253, s[56:57]
	s_add_u32 s56, s56, 0x20000
	s_addc_u32 s57, s57, 0
	s_add_u32 m0, s62, 0x4000
	s_nop 0
	global_load_lds_dwordx4 v252, s[56:57]
	s_add_u32 m0, s62, 0x5000
	s_nop 0
	global_load_lds_dwordx4 v253, s[56:57]
	s_add_u32 s56, s56, 0x20000
	s_addc_u32 s57, s57, 0
	s_add_u32 m0, s62, 0x6000
	s_nop 0
	global_load_lds_dwordx4 v252, s[56:57]
	s_add_u32 m0, s62, 0x7000
	s_nop 0
	global_load_lds_dwordx4 v253, s[56:57]
	s_sub_u32 s56, s56, 0x60000
	s_subb_u32 s57, s57, 0
	s_add_u32 m0, s62, 0x8000
	s_nop 0
	global_load_lds_dwordx4 v252, s[58:59]
	s_add_u32 m0, s62, 0x9000
	s_nop 0
	global_load_lds_dwordx4 v253, s[58:59]
	s_add_u32 s58, s58, 0x20000
	s_addc_u32 s59, s59, 0
	s_add_u32 m0, s62, 0xa000
	s_nop 0
	global_load_lds_dwordx4 v252, s[58:59]
	s_add_u32 m0, s62, 0xb000
	s_nop 0
	global_load_lds_dwordx4 v253, s[58:59]
	s_sub_u32 s58, s58, 0x20000
	s_subb_u32 s59, s59, 0
	v_add_u32_e32 v252, 0x80, v252
	v_add_u32_e32 v253, 0x80, v253
	global_load_dword v223, v222, s[56:57] offset:256
	v_add_u32_e32 v222, 0x80, v222
	s_waitcnt vmcnt(1)
	s_barrier
	ds_read_b128 v[148:151], v215 offset:32768
	ds_read_b128 v[152:155], v215 offset:34816
	ds_read_b128 v[156:159], v213
	ds_read_b128 v[160:163], v213 offset:2048
	ds_read_b128 v[164:167], v215 offset:40960
	ds_read_b128 v[168:171], v215 offset:43008
	s_waitcnt lgkmcnt(3)
	v_mfma_f32_16x16x32_bf16 v[140:143], v[148:151], v[156:159], v[140:143]
	v_mfma_f32_16x16x32_bf16 v[136:139], v[152:155], v[156:159], v[136:139]
	s_waitcnt lgkmcnt(1)
	v_mfma_f32_16x16x32_bf16 v[132:135], v[164:167], v[156:159], v[132:135]
	s_waitcnt lgkmcnt(0)
	v_mfma_f32_16x16x32_bf16 v[128:131], v[168:171], v[156:159], v[128:131]
	v_mfma_f32_16x16x32_bf16 v[124:127], v[148:151], v[160:163], v[124:127]
	v_mfma_f32_16x16x32_bf16 v[120:123], v[152:155], v[160:163], v[120:123]
	v_mfma_f32_16x16x32_bf16 v[116:119], v[164:167], v[160:163], v[116:119]
	v_mfma_f32_16x16x32_bf16 v[104:107], v[168:171], v[160:163], v[104:107]
	ds_read_b128 v[156:159], v213 offset:4096
	ds_read_b128 v[160:163], v213 offset:6144
	s_waitcnt lgkmcnt(1)
	v_mfma_f32_16x16x32_bf16 v[88:91], v[148:151], v[156:159], v[88:91]
	v_mfma_f32_16x16x32_bf16 v[84:87], v[152:155], v[156:159], v[84:87]
	v_mfma_f32_16x16x32_bf16 v[80:83], v[164:167], v[156:159], v[80:83]
	v_mfma_f32_16x16x32_bf16 v[76:79], v[168:171], v[156:159], v[76:79]
	s_waitcnt lgkmcnt(0)
	v_mfma_f32_16x16x32_bf16 v[72:75], v[148:151], v[160:163], v[72:75]
	v_mfma_f32_16x16x32_bf16 v[68:71], v[152:155], v[160:163], v[68:71]
	v_mfma_f32_16x16x32_bf16 v[64:67], v[164:167], v[160:163], v[64:67]
	v_mfma_f32_16x16x32_bf16 v[60:63], v[168:171], v[160:163], v[60:63]
	ds_read_b128 v[156:159], v213 offset:8192
	ds_read_b128 v[160:163], v213 offset:10240
	s_waitcnt lgkmcnt(1)
	v_mfma_f32_16x16x32_bf16 v[44:47], v[148:151], v[156:159], v[44:47]
	v_mfma_f32_16x16x32_bf16 v[40:43], v[152:155], v[156:159], v[40:43]
	v_mfma_f32_16x16x32_bf16 v[36:39], v[164:167], v[156:159], v[36:39]
	v_mfma_f32_16x16x32_bf16 v[32:35], v[168:171], v[156:159], v[32:35]
	s_waitcnt lgkmcnt(0)
	v_mfma_f32_16x16x32_bf16 v[28:31], v[148:151], v[160:163], v[28:31]
	v_mfma_f32_16x16x32_bf16 v[24:27], v[152:155], v[160:163], v[24:27]
	v_mfma_f32_16x16x32_bf16 v[20:23], v[164:167], v[160:163], v[20:23]
	v_mfma_f32_16x16x32_bf16 v[52:55], v[168:171], v[160:163], v[52:55]
	ds_read_b128 v[156:159], v213 offset:12288
	ds_read_b128 v[160:163], v213 offset:14336
	ds_read_b128 v[172:175], v206 offset:32768
	ds_read_b128 v[180:183], v206 offset:34816
	s_waitcnt lgkmcnt(3)
	v_mfma_f32_16x16x32_bf16 v[48:51], v[148:151], v[156:159], v[48:51]
	v_mfma_f32_16x16x32_bf16 v[56:59], v[152:155], v[156:159], v[56:59]
	s_waitcnt lgkmcnt(2)
	v_mfma_f32_16x16x32_bf16 v[100:103], v[148:151], v[160:163], v[100:103]
	v_mfma_f32_16x16x32_bf16 v[96:99], v[152:155], v[160:163], v[96:99]
	ds_read_b128 v[148:151], v0
	ds_read_b128 v[152:155], v0 offset:2048
	ds_read_b128 v[192:195], v206 offset:40960
	ds_read_b128 v[196:199], v206 offset:43008
	s_waitcnt lgkmcnt(3)
	v_mfma_f32_16x16x32_bf16 v[140:143], v[172:175], v[148:151], v[140:143]
	v_mfma_f32_16x16x32_bf16 v[136:139], v[180:183], v[148:151], v[136:139]
	s_waitcnt lgkmcnt(1)
	v_mfma_f32_16x16x32_bf16 v[132:135], v[192:195], v[148:151], v[132:135]
	s_waitcnt lgkmcnt(0)
	v_mfma_f32_16x16x32_bf16 v[128:131], v[196:199], v[148:151], v[128:131]
	v_mfma_f32_16x16x32_bf16 v[124:127], v[172:175], v[152:155], v[124:127]
	v_mfma_f32_16x16x32_bf16 v[120:123], v[180:183], v[152:155], v[120:123]
	v_mfma_f32_16x16x32_bf16 v[116:119], v[192:195], v[152:155], v[116:119]
	v_mfma_f32_16x16x32_bf16 v[104:107], v[196:199], v[152:155], v[104:107]
	ds_read_b128 v[148:151], v0 offset:4096
	ds_read_b128 v[152:155], v0 offset:6144
	v_mfma_f32_16x16x32_bf16 v[112:115], v[164:167], v[156:159], v[112:115]
	v_mfma_f32_16x16x32_bf16 v[92:95], v[164:167], v[160:163], v[92:95]
	v_mfma_f32_16x16x32_bf16 v[108:111], v[168:171], v[156:159], v[108:111]
	v_mfma_f32_16x16x32_bf16 v[144:147], v[168:171], v[160:163], v[144:147]
	s_waitcnt lgkmcnt(0)
; template <int MI, bool SWAP, bool F8 = false>
; __device__ __forceinline__ void gemm_core(const bf16_t* __restrict__ A, int lda, const bf16_t* __restrict__ B, int ldb,
;                                           int K, char* smem, f32x4 (&acc)[MI][4]) {
;     ...
;   for (int kt = 0; kt < nk; ++kt) {
;     __syncthreads();
; #pragma unroll
;     for (int i = 0; i < MI; ++i) *(u32x4*)(smem + woff + i * 4096) = ra[i];
; #pragma unroll
;     for (int i = 0; i < 4; ++i) *(u32x4*)(smem + 32768 + woff + i * 4096) = rb[i];
;     __syncthreads();
;     if (kt + 1 < nk) {
; #pragma unroll
;       for (int i = 0; i < MI; ++i) ra[i] = *(const u32x4*)(ap + (size_t)(32 * i) * lda + (kt + 1) * 64);
; #pragma unroll
;       for (int i = 0; i < 4; ++i) rb[i] = *(const u32x4*)(bp + (size_t)(32 * i) * ldb + (kt + 1) * 64);
;     }
;     if (F8) {
;       const int c0 = (g ^ (li & 7)) << 4, c1 = ((4 + g) ^ (li & 7)) << 4;
;       i32x8 wf8[4];
; #pragma unroll
;       for (int j = 0; j < 4; ++j) {
;         const char* rp = smem + wrow + ((j & 1) * 16 + (j >> 1) * 64) * 128;
;         const u32x4 lo = *(const u32x4*)(rp + c0), hi = *(const u32x4*)(rp + c1);
;         wf8[j] = (i32x8){(int)lo.x, (int)lo.y, (int)lo.z, (int)lo.w, (int)hi.x, (int)hi.y, (int)hi.z, (int)hi.w};
;       }
; #pragma unroll
;       for (int i = 0; i < MI; ++i) {
;         const char* rp = smem + xrow + i * 2048;
;         const u32x4 lo = *(const u32x4*)(rp + c0), hi = *(const u32x4*)(rp + c1);
;         const i32x8 xf8 = {(int)lo.x, (int)lo.y, (int)lo.z, (int)lo.w, (int)hi.x, (int)hi.y, (int)hi.z, (int)hi.w};
; #pragma unroll
;         for (int j = 0; j < 4; ++j)
;           acc[i][j] = __builtin_amdgcn_mfma_scale_f32_16x16x128_f8f6f4(wf8[j], xf8, acc[i][j], 0, 0, 0, 0x77777777, 0, 0x7f7f7f7f);
;       }
;     } else {
; #pragma unroll
;     for (int kk = 0; kk < 2; ++kk) {
;       const int ch = ((kk * 4 + g) ^ (li & 7)) << 4;
;       bf16x8 xf[MI], wf[4];
; #pragma unroll
;       for (int j = 0; j < 4; ++j) wf[j] = *(const bf16x8*)(smem + wrow + ((j & 1) * 16 + (j >> 1) * 64) * 128 + ch);
; #pragma unroll
;       for (int i = 0; i < MI; ++i) xf[i] = *(const bf16x8*)(smem + xrow + i * 2048 + ch);
; #pragma unroll
;       for (int i = 0; i < MI; ++i)
; #pragma unroll
;         for (int j = 0; j < 4; ++j) {
	v_mfma_f32_16x16x32_bf16 v[72:75], v[172:175], v[152:155], v[72:75]
	v_mfma_f32_16x16x32_bf16 v[68:71], v[180:183], v[152:155], v[68:71]
	v_mfma_f32_16x16x32_bf16 v[64:67], v[192:195], v[152:155], v[64:67]
	v_mfma_f32_16x16x32_bf16 v[60:63], v[196:199], v[152:155], v[60:63]
	v_mfma_f32_16x16x32_bf16 v[88:91], v[172:175], v[148:151], v[88:91]
	v_mfma_f32_16x16x32_bf16 v[84:87], v[180:183], v[148:151], v[84:87]
	v_mfma_f32_16x16x32_bf16 v[80:83], v[192:195], v[148:151], v[80:83]
	v_mfma_f32_16x16x32_bf16 v[76:79], v[196:199], v[148:151], v[76:79]
	ds_read_b128 v[148:151], v0 offset:8192
	ds_read_b128 v[156:159], v0 offset:10240
	ds_read_b128 v[160:163], v0 offset:12288
	ds_read_b128 v[200:203], v0 offset:14336
	s_waitcnt lgkmcnt(3)
	v_mfma_f32_16x16x32_bf16 v[44:47], v[172:175], v[148:151], v[44:47]
	v_mfma_f32_16x16x32_bf16 v[40:43], v[180:183], v[148:151], v[40:43]
	v_mfma_f32_16x16x32_bf16 v[36:39], v[192:195], v[148:151], v[36:39]
	v_mfma_f32_16x16x32_bf16 v[32:35], v[196:199], v[148:151], v[32:35]
	s_waitcnt lgkmcnt(2)
	v_mfma_f32_16x16x32_bf16 v[28:31], v[172:175], v[156:159], v[28:31]
	v_mfma_f32_16x16x32_bf16 v[24:27], v[180:183], v[156:159], v[24:27]
	v_mfma_f32_16x16x32_bf16 v[20:23], v[192:195], v[156:159], v[20:23]
	v_mfma_f32_16x16x32_bf16 v[52:55], v[196:199], v[156:159], v[52:55]
	s_waitcnt lgkmcnt(1)
	v_mfma_f32_16x16x32_bf16 v[48:51], v[172:175], v[160:163], v[48:51]
	v_mfma_f32_16x16x32_bf16 v[56:59], v[180:183], v[160:163], v[56:59]
	v_mfma_f32_16x16x32_bf16 v[112:115], v[192:195], v[160:163], v[112:115]
	v_mfma_f32_16x16x32_bf16 v[108:111], v[196:199], v[160:163], v[108:111]
	s_waitcnt lgkmcnt(0)
	v_mfma_f32_16x16x32_bf16 v[100:103], v[172:175], v[200:203], v[100:103]
	v_mfma_f32_16x16x32_bf16 v[96:99], v[180:183], v[200:203], v[96:99]
	v_mfma_f32_16x16x32_bf16 v[92:95], v[192:195], v[200:203], v[92:95]
	v_mfma_f32_16x16x32_bf16 v[144:147], v[196:199], v[200:203], v[144:147]
	s_add_u32 s22, s22, 0x80
	s_addc_u32 s23, s23, 0
	s_cmpk_lg_i32 s22, 0x780
	s_cbranch_scc1 .LBB0_120
	s_barrier
	s_mov_b32 m0, s62
	s_nop 0
	global_load_lds_dwordx4 v252, s[56:57]
	s_add_u32 m0, s62, 0x1000
	s_nop 0
	global_load_lds_dwordx4 v253, s[56:57]
	s_add_u32 s56, s56, 0x20000
	s_addc_u32 s57, s57, 0
	s_add_u32 m0, s62, 0x2000
	s_nop 0
	global_load_lds_dwordx4 v252, s[56:57]
	s_add_u32 m0, s62, 0x3000
	s_nop 0
	global_load_lds_dwordx4 v253, s[56:57]
	s_add_u32 s56, s56, 0x20000
	s_addc_u32 s57, s57, 0
	s_add_u32 m0, s62, 0x4000
	s_nop 0
	global_load_lds_dwordx4 v252, s[56:57]
	s_add_u32 m0, s62, 0x5000
	s_nop 0
	global_load_lds_dwordx4 v253, s[56:57]
	s_add_u32 s56, s56, 0x20000
	s_addc_u32 s57, s57, 0
	s_add_u32 m0, s62, 0x6000
	s_nop 0
	global_load_lds_dwordx4 v252, s[56:57]
	s_add_u32 m0, s62, 0x7000
	s_nop 0
	global_load_lds_dwordx4 v253, s[56:57]
	s_sub_u32 s56, s56, 0x60000
	s_subb_u32 s57, s57, 0
	s_add_u32 m0, s62, 0x8000
	s_nop 0
	global_load_lds_dwordx4 v252, s[58:59]
	s_add_u32 m0, s62, 0x9000
	s_nop 0
	global_load_lds_dwordx4 v253, s[58:59]
	s_add_u32 s58, s58, 0x20000
	s_addc_u32 s59, s59, 0
	s_add_u32 m0, s62, 0xa000
	s_nop 0
	global_load_lds_dwordx4 v252, s[58:59]
	s_add_u32 m0, s62, 0xb000
	s_nop 0
	global_load_lds_dwordx4 v253, s[58:59]
	s_sub_u32 s58, s58, 0x20000
	s_subb_u32 s59, s59, 0
	s_waitcnt vmcnt(0)
	s_barrier
	v_bfe_u32 v12, v208, 4, 1
	v_mul_u32_u24_e32 v12, 24, v12
	v_mov_b32_e32 v13, 0
	ds_read_b128 v[148:151], v215 offset:32768
	ds_read_b128 v[152:155], v215 offset:34816
	ds_read_b128 v[156:159], v215 offset:40960
	ds_read_b128 v[160:163], v215 offset:43008
	ds_read_b128 v[164:167], v213
	ds_read_b128 v[168:171], v213 offset:2048
	ds_read_b128 v[172:175], v213 offset:4096
	ds_read_b128 v[176:179], v213 offset:6144
	ds_read_b128 v[180:183], v213 offset:8192
	ds_read_b128 v[184:187], v213 offset:10240
	ds_read_b128 v[188:191], v213 offset:12288
	ds_read_b128 v[192:195], v213 offset:14336
	s_waitcnt lgkmcnt(7)
	v_mfma_f32_16x16x32_bf16 v[140:143], v[148:151], v[164:167], v[140:143]
	s_mul_hi_i32 s11, s10, 0x180000
	s_mul_i32 s10, s10, 0x180000
	s_add_u32 s22, s8, s10
	v_mfma_f32_16x16x32_bf16 v[136:139], v[152:155], v[164:167], v[136:139]
	s_addc_u32 s23, s9, s11
	s_lshl_b64 s[10:11], s[20:21], 1
	s_add_u32 s10, s22, s10
	v_mfma_f32_16x16x32_bf16 v[132:135], v[156:159], v[164:167], v[132:135]
	s_addc_u32 s11, s23, s11
	s_movk_i32 s20, 0x1800
	s_add_i32 s28, s28, s78
	v_mfma_f32_16x16x32_bf16 v[128:131], v[160:163], v[164:167], v[128:131]
	s_add_i32 s27, s27, s71
	s_cmpk_gt_i32 s28, 0x5ff
	s_waitcnt lgkmcnt(6)
	v_mfma_f32_16x16x32_bf16 v[124:127], v[148:151], v[168:171], v[124:127]
	v_mfma_f32_16x16x32_bf16 v[120:123], v[152:155], v[168:171], v[120:123]
	v_mfma_f32_16x16x32_bf16 v[116:119], v[156:159], v[168:171], v[116:119]
	v_mfma_f32_16x16x32_bf16 v[104:107], v[160:163], v[168:171], v[104:107]
	s_waitcnt lgkmcnt(5)
	v_mfma_f32_16x16x32_bf16 v[88:91], v[148:151], v[172:175], v[88:91]
	v_mfma_f32_16x16x32_bf16 v[84:87], v[152:155], v[172:175], v[84:87]
	v_mfma_f32_16x16x32_bf16 v[80:83], v[156:159], v[172:175], v[80:83]
	v_mfma_f32_16x16x32_bf16 v[76:79], v[160:163], v[172:175], v[76:79]
	s_waitcnt lgkmcnt(4)
	v_mfma_f32_16x16x32_bf16 v[72:75], v[148:151], v[176:179], v[72:75]
	v_mfma_f32_16x16x32_bf16 v[68:71], v[152:155], v[176:179], v[68:71]
	v_mfma_f32_16x16x32_bf16 v[64:67], v[156:159], v[176:179], v[64:67]
	v_mfma_f32_16x16x32_bf16 v[60:63], v[160:163], v[176:179], v[60:63]
	s_waitcnt lgkmcnt(3)
	v_mfma_f32_16x16x32_bf16 v[44:47], v[148:151], v[180:183], v[44:47]
	v_mfma_f32_16x16x32_bf16 v[40:43], v[152:155], v[180:183], v[40:43]
	v_mfma_f32_16x16x32_bf16 v[36:39], v[156:159], v[180:183], v[36:39]
	v_mfma_f32_16x16x32_bf16 v[32:35], v[160:163], v[180:183], v[32:35]
	s_waitcnt lgkmcnt(2)
; template <int MI, bool SWAP, bool F8 = false>
; __device__ __forceinline__ void gemm_core(const bf16_t* __restrict__ A, int lda, const bf16_t* __restrict__ B, int ldb,
;                                           int K, char* smem, f32x4 (&acc)[MI][4]) {
;     ...
;     for (int kk = 0; kk < 2; ++kk) {
;       const int ch = ((kk * 4 + g) ^ (li & 7)) << 4;
;       bf16x8 xf[MI], wf[4];
; #pragma unroll
;       for (int j = 0; j < 4; ++j) wf[j] = *(const bf16x8*)(smem + wrow + ((j & 1) * 16 + (j >> 1) * 64) * 128 + ch);
; #pragma unroll
;       for (int i = 0; i < MI; ++i) xf[i] = *(const bf16x8*)(smem + xrow + i * 2048 + ch);
; #pragma unroll
;       for (int i = 0; i < MI; ++i)
; #pragma unroll
;         for (int j = 0; j < 4; ++j) {
;           if (SWAP) acc[i][j] = __builtin_amdgcn_mfma_f32_16x16x32_bf16(xf[i], wf[j], acc[i][j], 0, 0, 0);
;           else acc[i][j] = __builtin_amdgcn_mfma_f32_16x16x32_bf16(wf[j], xf[i], acc[i][j], 0, 0, 0);
;         }
; template <int MI, bool F8 = false>
; __device__ void gemm_tile_bf16(const bf16_t* A, int lda, const bf16_t* B, int ldb, int K, bf16_t* C, int ldc, char* smem) {
;     ...
; #pragma unroll
;   for (int i = 0; i < MI; ++i)
; #pragma unroll
;     for (int j = 0; j < 4; ++j) {
;       u32x2 v;
;       v.x = pk_bf16(acc[i][j][0], acc[i][j][1]);
;       v.y = pk_bf16(acc[i][j][2], acc[i][j][3]);
;       *(u32x2*)(C + (size_t)MROW(i) * ldc + NCOL(j)) = v;
;     }
	v_mfma_f32_16x16x32_bf16 v[28:31], v[148:151], v[184:187], v[28:31]
	v_mfma_f32_16x16x32_bf16 v[24:27], v[152:155], v[184:187], v[24:27]
	v_mfma_f32_16x16x32_bf16 v[20:23], v[156:159], v[184:187], v[20:23]
	v_mfma_f32_16x16x32_bf16 v[52:55], v[160:163], v[184:187], v[52:55]
	s_waitcnt lgkmcnt(1)
	v_mfma_f32_16x16x32_bf16 v[48:51], v[148:151], v[188:191], v[48:51]
	v_mfma_f32_16x16x32_bf16 v[164:167], v[152:155], v[188:191], v[56:59]
	v_mfma_f32_16x16x32_bf16 v[168:171], v[156:159], v[188:191], v[112:115]
	v_mfma_f32_16x16x32_bf16 v[172:175], v[160:163], v[188:191], v[108:111]
	s_waitcnt lgkmcnt(0)
	v_mfma_f32_16x16x32_bf16 v[148:151], v[148:151], v[192:195], v[100:103]
	v_mfma_f32_16x16x32_bf16 v[152:155], v[152:155], v[192:195], v[96:99]
	v_mfma_f32_16x16x32_bf16 v[156:159], v[156:159], v[192:195], v[92:95]
	v_mfma_f32_16x16x32_bf16 v[144:147], v[160:163], v[192:195], v[144:147]
	ds_read_b128 v[160:163], v206 offset:32768
	ds_read_b128 v[176:179], v206 offset:34816
	ds_read_b128 v[180:183], v206 offset:40960
	ds_read_b128 v[184:187], v206 offset:43008
	ds_read_b128 v[56:59], v0
	ds_read_b128 v[92:95], v0 offset:2048
	ds_read_b128 v[96:99], v0 offset:4096
	ds_read_b128 v[188:191], v0 offset:6144
	ds_read_b128 v[192:195], v0 offset:8192
	ds_read_b128 v[196:199], v0 offset:10240
	ds_read_b128 v[200:203], v0 offset:12288
	ds_read_b128 v[204:207], v0 offset:14336
	s_waitcnt lgkmcnt(7)
	v_mfma_f32_16x16x32_bf16 v[140:143], v[160:163], v[56:59], v[140:143]
	v_mfma_f32_16x16x32_bf16 v[136:139], v[176:179], v[56:59], v[136:139]
	v_mfma_f32_16x16x32_bf16 v[132:135], v[180:183], v[56:59], v[132:135]
	s_nop 5
	v_cvt_pk_bf16_f32 v140, v140, v141
	v_cvt_pk_bf16_f32 v141, v142, v143
	v_cvt_pk_bf16_f32 v136, v136, v137
	v_mfma_f32_16x16x32_bf16 v[128:131], v[184:187], v[56:59], v[128:131]
	v_cvt_pk_bf16_f32 v137, v138, v139
	v_cvt_pk_bf16_f32 v132, v132, v133
	v_cvt_pk_bf16_f32 v133, v134, v135
	s_waitcnt lgkmcnt(2)
	v_mfma_f32_16x16x32_bf16 v[56:59], v[180:183], v[196:199], v[20:23]
	s_waitcnt lgkmcnt(0)
	v_mfma_f32_16x16x32_bf16 v[20:23], v[184:187], v[204:207], v[144:147]
	s_nop 0
	v_cvt_pk_bf16_f32 v128, v128, v129
	v_cvt_pk_bf16_f32 v129, v130, v131
	s_nop 2
	v_cvt_pk_bf16_f32 v56, v56, v57
	v_mov_b32_e32 v146, v208
	v_mfma_f32_16x16x32_bf16 v[124:127], v[160:163], v[92:95], v[124:127]
	v_lshrrev_b32_e32 v0, 1, v146
	v_and_b32_e32 v0, 32, v0
	v_lshrrev_b32_e32 v2, 2, v146
	v_and_b32_e32 v147, 0xffffff8f, v146
	v_and_or_b32 v0, v2, 12, v0
	v_mov_b64_e32 v[2:3], s[10:11]
	v_mfma_f32_16x16x32_bf16 v[216:219], v[180:183], v[92:95], v[116:119]
	v_mad_i64_i32 v[144:145], s[10:11], v147, s20, v[2:3]
	v_lshlrev_b32_e32 v0, 1, v0
	v_mfma_f32_16x16x32_bf16 v[116:119], v[184:187], v[92:95], v[104:107]
	v_lshl_add_u64 v[142:143], v[144:145], 0, v[0:1]
	global_store_dwordx2 v[142:143], v[128:129], off offset:160
	v_or_b32_e32 v128, 16, v147
	v_mfma_f32_16x16x32_bf16 v[112:115], v[160:163], v[96:99], v[88:91]
	v_mad_i64_i32 v[128:129], s[10:11], v128, s20, v[2:3]
	v_cvt_pk_bf16_f32 v124, v124, v125
	v_mfma_f32_16x16x32_bf16 v[100:103], v[184:187], v[96:99], v[76:79]
	v_cvt_pk_bf16_f32 v125, v126, v127
	v_lshl_add_u64 v[126:127], v[128:129], 0, v[0:1]
	v_cvt_pk_bf16_f32 v116, v116, v117
	v_cvt_pk_bf16_f32 v117, v118, v119
	global_store_dwordx2 v[126:127], v[116:117], off offset:160
	v_or_b32_e32 v116, 32, v147
	v_mfma_f32_16x16x32_bf16 v[108:111], v[176:179], v[96:99], v[84:87]
	v_mad_i64_i32 v[116:117], s[10:11], v116, s20, v[2:3]
	v_cvt_pk_bf16_f32 v112, v112, v113
	v_mfma_f32_16x16x32_bf16 v[104:107], v[180:183], v[96:99], v[80:83]
	v_cvt_pk_bf16_f32 v113, v114, v115
	v_lshl_add_u64 v[114:115], v[116:117], 0, v[0:1]
	v_cvt_pk_bf16_f32 v100, v100, v101
	v_mfma_f32_16x16x32_bf16 v[96:99], v[160:163], v[188:191], v[72:75]
	v_cvt_pk_bf16_f32 v101, v102, v103
	global_store_dwordx2 v[114:115], v[100:101], off offset:160
	v_or_b32_e32 v100, 48, v147
	v_mfma_f32_16x16x32_bf16 v[84:87], v[184:187], v[188:191], v[60:63]
	v_mad_i64_i32 v[100:101], s[10:11], v100, s20, v[2:3]
	s_nop 2
	v_cvt_pk_bf16_f32 v96, v96, v97
	v_mfma_f32_16x16x32_bf16 v[120:123], v[176:179], v[92:95], v[120:123]
	v_cvt_pk_bf16_f32 v97, v98, v99
	v_lshl_add_u64 v[98:99], v[100:101], 0, v[0:1]
	v_cvt_pk_bf16_f32 v84, v84, v85
	v_mfma_f32_16x16x32_bf16 v[92:95], v[176:179], v[188:191], v[68:71]
	v_cvt_pk_bf16_f32 v85, v86, v87
	global_store_dwordx2 v[98:99], v[84:85], off offset:160
	v_or_b32_e32 v84, 64, v147
	v_mfma_f32_16x16x32_bf16 v[80:83], v[160:163], v[192:195], v[44:47]
	v_mad_i64_i32 v[84:85], s[10:11], v84, s20, v[2:3]
	v_cvt_pk_bf16_f32 v120, v120, v121
	v_mfma_f32_16x16x32_bf16 v[68:71], v[184:187], v[192:195], v[32:35]
	v_cvt_pk_bf16_f32 v121, v122, v123
	s_nop 3
	v_cvt_pk_bf16_f32 v80, v80, v81
	v_cvt_pk_bf16_f32 v81, v82, v83
	v_mfma_f32_16x16x32_bf16 v[88:91], v[180:183], v[188:191], v[64:67]
	v_lshl_add_u64 v[82:83], v[84:85], 0, v[0:1]
	v_cvt_pk_bf16_f32 v68, v68, v69
	v_cvt_pk_bf16_f32 v69, v70, v71
	v_mfma_f32_16x16x32_bf16 v[64:67], v[160:163], v[196:199], v[28:31]
; template <int MI, bool F8 = false>
; __device__ void gemm_tile_bf16(const bf16_t* A, int lda, const bf16_t* B, int ldb, int K, bf16_t* C, int ldc, char* smem) {
;     ...
; #pragma unroll
;   for (int i = 0; i < MI; ++i)
; #pragma unroll
;     for (int j = 0; j < 4; ++j) {
;       u32x2 v;
;       v.x = pk_bf16(acc[i][j][0], acc[i][j][1]);
;       v.y = pk_bf16(acc[i][j][2], acc[i][j][3]);
;       *(u32x2*)(C + (size_t)MROW(i) * ldc + NCOL(j)) = v;
;     }
	global_store_dwordx2 v[82:83], v[68:69], off offset:160
	v_or_b32_e32 v68, 0x50, v147
	v_mad_i64_i32 v[68:69], s[10:11], v68, s20, v[2:3]
	v_mfma_f32_16x16x32_bf16 v[52:55], v[184:187], v[196:199], v[52:55]
	s_nop 3
	v_cvt_pk_bf16_f32 v64, v64, v65
	v_cvt_pk_bf16_f32 v65, v66, v67
	v_lshl_add_u64 v[66:67], v[68:69], 0, v[0:1]
	v_mfma_f32_16x16x32_bf16 v[72:75], v[180:183], v[192:195], v[36:39]
	global_store_dwordx2 v[126:127], v[120:121], off offset:32
	v_cvt_pk_bf16_f32 v52, v52, v53
	v_cvt_pk_bf16_f32 v53, v54, v55
	v_mfma_f32_16x16x32_bf16 v[48:51], v[160:163], v[200:203], v[48:51]
	global_store_dwordx2 v[66:67], v[52:53], off offset:160
	v_or_b32_e32 v52, 0x60, v147
	v_mad_i64_i32 v[52:53], s[10:11], v52, s20, v[2:3]
	v_mfma_f32_16x16x32_bf16 v[36:39], v[184:187], v[200:203], v[172:175]
	s_nop 3
	v_cvt_pk_bf16_f32 v48, v48, v49
	v_cvt_pk_bf16_f32 v49, v50, v51
	v_lshl_add_u64 v[50:51], v[52:53], 0, v[0:1]
	v_mfma_f32_16x16x32_bf16 v[76:79], v[176:179], v[192:195], v[40:43]
	v_cvt_pk_bf16_f32 v120, v216, v217
	v_cvt_pk_bf16_f32 v36, v36, v37
	v_cvt_pk_bf16_f32 v37, v38, v39
	v_mfma_f32_16x16x32_bf16 v[60:63], v[176:179], v[196:199], v[24:27]
	global_store_dwordx2 v[50:51], v[36:37], off offset:160
	v_or_b32_e32 v36, 0x70, v146
	v_mad_i64_i32 v[2:3], s[10:11], v36, s20, v[2:3]
	v_mfma_f32_16x16x32_bf16 v[44:47], v[176:179], v[200:203], v[164:167]
	v_cvt_pk_bf16_f32 v121, v218, v219
	v_cvt_pk_bf16_f32 v108, v108, v109
	v_cvt_pk_bf16_f32 v109, v110, v111
	v_mfma_f32_16x16x32_bf16 v[40:43], v[180:183], v[200:203], v[168:171]
	v_cvt_pk_bf16_f32 v104, v104, v105
	v_cvt_pk_bf16_f32 v105, v106, v107
	v_cvt_pk_bf16_f32 v92, v92, v93
	v_mfma_f32_16x16x32_bf16 v[32:35], v[160:163], v[204:207], v[148:151]
	v_cvt_pk_bf16_f32 v93, v94, v95
	v_cvt_pk_bf16_f32 v88, v88, v89
	v_cvt_pk_bf16_f32 v89, v90, v91
	v_mfma_f32_16x16x32_bf16 v[28:31], v[176:179], v[204:207], v[152:155]
	v_cvt_pk_bf16_f32 v76, v76, v77
	v_cvt_pk_bf16_f32 v77, v78, v79
	v_cvt_pk_bf16_f32 v72, v72, v73
	v_mfma_f32_16x16x32_bf16 v[24:27], v[180:183], v[204:207], v[156:159]
	v_cvt_pk_bf16_f32 v73, v74, v75
	v_cvt_pk_bf16_f32 v60, v60, v61
	v_cvt_pk_bf16_f32 v61, v62, v63
	v_cvt_pk_bf16_f32 v57, v58, v59
	v_cvt_pk_bf16_f32 v44, v44, v45
	v_cvt_pk_bf16_f32 v45, v46, v47
	v_cvt_pk_bf16_f32 v40, v40, v41
	v_cvt_pk_bf16_f32 v41, v42, v43
	v_cvt_pk_bf16_f32 v32, v32, v33
	v_cvt_pk_bf16_f32 v33, v34, v35
	v_lshl_add_u64 v[2:3], v[2:3], 0, v[0:1]
	v_cvt_pk_bf16_f32 v28, v28, v29
	v_cvt_pk_bf16_f32 v29, v30, v31
	v_cvt_pk_bf16_f32 v24, v24, v25
	v_cvt_pk_bf16_f32 v25, v26, v27
	v_cvt_pk_bf16_f32 v20, v20, v21
	v_cvt_pk_bf16_f32 v21, v22, v23
	v_mov_b64_e32 v[4:5], v[140:141]
	v_mov_b64_e32 v[6:7], v[136:137]
	s_nop 1
	v_permlane16_swap_b32_e32 v4, v6
	v_permlane16_swap_b32_e32 v5, v7
	v_lshl_add_u64 v[14:15], v[142:143], 0, v[12:13]
	global_store_dwordx4 v[14:15], v[4:7], off
	global_store_dwordx2 v[142:143], v[132:133], off offset:128
	global_store_dwordx2 v[126:127], v[124:125], off
	global_store_dwordx2 v[126:127], v[120:121], off offset:128
	v_mov_b64_e32 v[8:9], v[112:113]
	v_mov_b64_e32 v[10:11], v[108:109]
	s_nop 1
	v_permlane16_swap_b32_e32 v8, v10
	v_permlane16_swap_b32_e32 v9, v11
	v_lshl_add_u64 v[14:15], v[114:115], 0, v[12:13]
	global_store_dwordx4 v[14:15], v[8:11], off
	global_store_dwordx2 v[114:115], v[104:105], off offset:128
	v_mov_b64_e32 v[4:5], v[96:97]
	v_mov_b64_e32 v[6:7], v[92:93]
	s_nop 1
	v_permlane16_swap_b32_e32 v4, v6
	v_permlane16_swap_b32_e32 v5, v7
	v_lshl_add_u64 v[14:15], v[98:99], 0, v[12:13]
	global_store_dwordx4 v[14:15], v[4:7], off
	global_store_dwordx2 v[98:99], v[88:89], off offset:128
	v_mov_b64_e32 v[8:9], v[80:81]
	v_mov_b64_e32 v[10:11], v[76:77]
	s_nop 1
	v_permlane16_swap_b32_e32 v8, v10
	v_permlane16_swap_b32_e32 v9, v11
	v_lshl_add_u64 v[14:15], v[82:83], 0, v[12:13]
	global_store_dwordx4 v[14:15], v[8:11], off
	global_store_dwordx2 v[82:83], v[72:73], off offset:128
	v_mov_b64_e32 v[4:5], v[64:65]
	v_mov_b64_e32 v[6:7], v[60:61]
	s_nop 1
	v_permlane16_swap_b32_e32 v4, v6
	v_permlane16_swap_b32_e32 v5, v7
	v_lshl_add_u64 v[14:15], v[66:67], 0, v[12:13]
	global_store_dwordx4 v[14:15], v[4:7], off
	global_store_dwordx2 v[66:67], v[56:57], off offset:128
	v_mov_b64_e32 v[8:9], v[48:49]
	v_mov_b64_e32 v[10:11], v[44:45]
	s_nop 1
	v_permlane16_swap_b32_e32 v8, v10
	v_permlane16_swap_b32_e32 v9, v11
	v_lshl_add_u64 v[14:15], v[50:51], 0, v[12:13]
	global_store_dwordx4 v[14:15], v[8:11], off
	global_store_dwordx2 v[50:51], v[40:41], off offset:128
	v_mov_b64_e32 v[4:5], v[32:33]
	v_mov_b64_e32 v[6:7], v[28:29]
	s_nop 1
	v_permlane16_swap_b32_e32 v4, v6
	v_permlane16_swap_b32_e32 v5, v7
	v_lshl_add_u64 v[14:15], v[2:3], 0, v[12:13]
	global_store_dwordx4 v[14:15], v[4:7], off
	v_mov_b64_e32 v[8:9], v[24:25]
	v_mov_b64_e32 v[10:11], v[20:21]
	s_nop 1
	v_permlane16_swap_b32_e32 v8, v10
	v_permlane16_swap_b32_e32 v9, v11
	v_lshl_add_u64 v[14:15], v[2:3], 0, v[12:13]
	global_store_dwordx4 v[14:15], v[8:11], off offset:128
	s_cbranch_scc0 .LBB0_119

; __device__ __forceinline__ int otid() { int t = threadIdx.x; asm volatile("" : "+v"(t)); return t; }
; __device__ __forceinline__ char* opaque(char* q) { size_t z = 0; asm volatile("" : "+s"(z)); return q + z; }
; template <int MI, bool SWAP, bool F8 = false>
; __device__ __forceinline__ void gemm_core(const bf16_t* __restrict__ A, int lda, const bf16_t* __restrict__ B, int ldb,
;                                           int K, char* smem, f32x4 (&acc)[MI][4]) {
;   const int tid = otid(), lane = tid & 63, w = tid >> 6, wm = w >> 1, wn = w & 1;
;   const int lr = tid >> 3, lc = tid & 7;
;   const int li = lane & 15, g = lane >> 4;
;   u32x4 ra[MI], rb[4];
;   const bf16_t* ap = A + (size_t)lr * lda + lc * 8;
;   const bf16_t* bp = B + (size_t)lr * ldb + lc * 8;
; #pragma unroll
;   for (int i = 0; i < MI; ++i)
; #pragma unroll
;     for (int j = 0; j < 4; ++j) acc[i][j] = (f32x4){0.f, 0.f, 0.f, 0.f};
;   const int nk = K >> 6;
; #pragma unroll
;   for (int i = 0; i < MI; ++i) ra[i] = *(const u32x4*)(ap + (size_t)(32 * i) * lda);
; #pragma unroll
;   for (int i = 0; i < 4; ++i) rb[i] = *(const u32x4*)(bp + (size_t)(32 * i) * ldb);
;   const int woff = lr * 128 + ((lc ^ (lr & 7)) << 4);
;   const int xrow = (wm * 16 * MI + li) * 128;
;   const int wrow = 32768 + (wn * 32 + li) * 128;
; __device__ void even_in_tile(const P& p, int li_even, int tm, int tn, char* smem) {
;   constexpr int MI = 8;
;   char* ws = opaque(p.ws);
;   const bf16_t* A = (const bf16_t*)(ws + OFF_XN) + (size_t)tm * 256 * 1024;
;   const bf16_t* B = (const bf16_t*)(ws + OFF_WEIN) + ((size_t)li_even * 3584 + (size_t)tn * 128) * 1024;
;   const int seg = tn >> 2, hd = tn & 3;
;   const int t0 = tm * 256, b = t0 >> 12, s0 = t0 & 4095, bh = b * 4 + hd;
;   bf16_t* R = (bf16_t*)(ws + OFF_R);
;   f32x4 acc[MI][4];
;   if (seg == 2 || seg == 5) {
;     gemm_core<MI, true>(A, 1024, B, 1024, 1024, smem, acc);
;     EPI_COORDS
;     bf16_t* dst = R + (seg == 2 ? R_MVT : R_RVT) + (size_t)bh * 128 * 4096;
; #pragma unroll
;     for (int i = 0; i < MI; ++i)
; #pragma unroll
;       for (int j = 0; j < 4; ++j) {
;         u32x2 v;
;         v.x = pk_bf16(acc[i][j][0], acc[i][j][1]);
;         v.y = pk_bf16(acc[i][j][2], acc[i][j][3]);
;         *(u32x2*)(dst + (size_t)NCOLS(j) * 4096 + s0 + MROWS(i)) = v;
;       }
;     return;
;   }
;   gemm_core<MI, false>(A, 1024, B, 1024, 1024, smem, acc);
.LBB0_299:
	s_ashr_i32 s25, s28, 2
	s_and_b32 s49, s24, 3
	s_lshl_b32 s54, s28, 8
	s_and_b32 s25, s25, -4
	s_and_b32 s44, s19, 56
	s_and_b32 s41, s54, 0xf00
	s_andn2_b64 vcc, exec, s[6:7]
	s_or_b32 s6, s25, s49
	s_cbranch_vccnz .LBB0_311
	s_waitcnt vmcnt(17)
	v_mov_b32_e32 v30, v208
	s_add_i32 s26, s43, s44
	v_ashrrev_i32_e32 v2, 3, v30
	v_ashrrev_i32_e32 v3, 31, v2
	v_lshlrev_b64 v[20:21], 11, v[2:3]
	v_lshlrev_b32_e32 v0, 4, v30
	v_lshl_add_u64 v[24:25], s[20:21], 0, v[20:21]
	v_and_b32_e32 v0, 0x70, v0
	v_lshl_add_u64 v[24:25], v[24:25], 0, v[0:1]
	v_add_co_u32_e32 v26, vcc, 0x10000, v24
	v_lshl_add_u64 v[22:23], s[22:23], 0, v[20:21]
	s_nop 0
	v_addc_co_u32_e32 v27, vcc, 0, v25, vcc
	v_lshrrev_b32_e32 v254, 3, v208
	v_and_b32_e32 v254, 7, v254
	v_xor_b32_e32 v252, v254, v208
	v_and_b32_e32 v252, 7, v252
	v_lshlrev_b32_e32 v252, 4, v252
	v_lshl_or_b32 v252, v254, 11, v252
	v_add_u32_e32 v253, 0x10000, v252
	v_lshrrev_b32_e32 v254, 6, v208
	s_nop 0
	v_readfirstlane_b32 s62, v254
	s_lshl_b32 s62, s62, 10
	v_readfirstlane_b32 s56, v24
	v_readfirstlane_b32 s57, v25
	v_lshrrev_b32_e32 v222, 6, v208
	v_and_b32_e32 v223, 63, v208
	v_mul_u32_u24_e32 v222, 56, v222
	v_add_u32_e32 v222, v222, v223
	v_lshlrev_b32_e32 v222, 11, v222
	v_add_co_u32_e32 v26, vcc, 0x20000, v24
	v_lshl_add_u64 v[22:23], v[22:23], 0, v[0:1]
	s_nop 0
	v_addc_co_u32_e32 v27, vcc, 0, v25, vcc
	v_add_co_u32_e32 v28, vcc, 0x30000, v24
	s_ashr_i32 s27, s26, 31
	s_nop 0
	v_addc_co_u32_e32 v29, vcc, 0, v25, vcc
	v_add_co_u32_e32 v26, vcc, 0x40000, v24
	v_and_b32_e32 v3, 15, v30
	s_nop 0
	v_addc_co_u32_e32 v27, vcc, 0, v25, vcc
	v_add_co_u32_e32 v28, vcc, 0x50000, v24
	s_lshl_b64 s[26:27], s[26:27], 19
	s_nop 0
	v_addc_co_u32_e32 v29, vcc, 0, v25, vcc
	v_add_co_u32_e32 v26, vcc, 0x60000, v24
	v_lshrrev_b32_e32 v31, 4, v30
	s_nop 0
	v_addc_co_u32_e32 v27, vcc, 0, v25, vcc
	v_add_co_u32_e32 v24, vcc, 0x70000, v24
	s_add_u32 s26, s8, s26
	s_nop 0
	v_addc_co_u32_e32 v25, vcc, 0, v25, vcc
	v_add_co_u32_e32 v24, vcc, s93, v22
	s_addc_u32 s27, s9, s27
	s_nop 0
	v_addc_co_u32_e32 v25, vcc, 0, v23, vcc
	s_nop 0
	v_readfirstlane_b32 s58, v22
	v_readfirstlane_b32 s59, v23
	v_add_co_u32_e32 v24, vcc, s46, v22
	v_bfe_u32 v0, v30, 4, 2
	s_nop 0
	v_addc_co_u32_e32 v25, vcc, 0, v23, vcc
	v_add_co_u32_e32 v22, vcc, s47, v22
	v_mov_b32_e32 v160, 0
	s_nop 0
	v_addc_co_u32_e32 v23, vcc, 0, v23, vcc
	v_lshlrev_b32_e32 v22, 7, v2
	v_xor_b32_e32 v2, v2, v30
	v_lshlrev_b32_e32 v2, 4, v2
	v_and_or_b32 v202, v2, s33, v22
	v_lshlrev_b32_e32 v2, 7, v30
	v_and_b32_e32 v203, 0xffffc780, v2
	v_lshrrev_b32_e32 v2, 1, v30
	v_and_or_b32 v2, v2, 32, v3
	v_and_b32_e32 v22, 7, v30
	v_lshlrev_b32_e32 v204, 7, v2
	v_bitop3_b32 v2, v31, v22, 3 bitop3:0x6c
	v_lshlrev_b32_e32 v205, 4, v2
	v_lshl_add_u64 v[2:3], s[26:27], 0, v[20:21]
	s_add_u32 s26, s8, s10
	v_bitop3_b32 v0, v0, v22, 4 bitop3:0x36
	s_addc_u32 s27, s9, s11
	v_lshlrev_b32_e32 v206, 4, v0
	v_lshlrev_b32_e32 v0, 4, v22
	v_lshl_add_u64 v[20:21], s[26:27], 0, v[20:21]
	v_lshl_add_u64 v[2:3], v[2:3], 0, v[0:1]
	v_lshl_add_u64 v[20:21], v[20:21], 0, v[0:1]
	v_lshl_add_u64 v[2:3], s[68:69], 0, v[2:3]
	v_lshl_add_u64 v[200:201], s[0:1], 0, v[20:21]
	s_mov_b64 s[26:27], 0
	v_mov_b32_e32 v161, v160
	v_mov_b32_e32 v162, v160
	v_mov_b32_e32 v163, v160
	v_mov_b32_e32 v20, v160
	v_mov_b32_e32 v21, v160
	v_mov_b32_e32 v22, v160
	v_mov_b32_e32 v23, v160
	s_waitcnt vmcnt(28)
	v_mov_b32_e32 v32, v160
	v_mov_b32_e32 v33, v160
	v_mov_b32_e32 v34, v160
	v_mov_b32_e32 v35, v160
	v_mov_b32_e32 v52, v160
	v_mov_b32_e32 v53, v160
	v_mov_b32_e32 v54, v160
	v_mov_b32_e32 v55, v160
	v_mov_b32_e32 v72, v160
	v_mov_b32_e32 v73, v160
	v_mov_b32_e32 v74, v160
	v_mov_b32_e32 v75, v160
	v_mov_b32_e32 v76, v160
	v_mov_b32_e32 v77, v160
	v_mov_b32_e32 v78, v160
	v_mov_b32_e32 v79, v160
	v_mov_b32_e32 v24, v160
	v_mov_b32_e32 v25, v160
	v_mov_b32_e32 v26, v160
	v_mov_b32_e32 v27, v160
	v_mov_b32_e32 v28, v160
	v_mov_b32_e32 v29, v160
	v_mov_b32_e32 v30, v160
	v_mov_b32_e32 v31, v160
	s_waitcnt vmcnt(27)
	v_mov_b32_e32 v36, v160
	v_mov_b32_e32 v37, v160
	v_mov_b32_e32 v38, v160
	v_mov_b32_e32 v39, v160
	s_waitcnt vmcnt(26)
	v_mov_b32_e32 v40, v160
	v_mov_b32_e32 v41, v160
	v_mov_b32_e32 v42, v160
	v_mov_b32_e32 v43, v160
	s_waitcnt vmcnt(25)
	v_mov_b32_e32 v44, v160
	v_mov_b32_e32 v45, v160
	v_mov_b32_e32 v46, v160
	v_mov_b32_e32 v47, v160
	s_waitcnt vmcnt(24)
	v_mov_b32_e32 v48, v160
	v_mov_b32_e32 v49, v160
	v_mov_b32_e32 v50, v160
	v_mov_b32_e32 v51, v160
	s_waitcnt vmcnt(23)
	v_mov_b32_e32 v56, v160
	v_mov_b32_e32 v57, v160
	v_mov_b32_e32 v58, v160
	v_mov_b32_e32 v59, v160
	v_mov_b32_e32 v60, v160
	v_mov_b32_e32 v61, v160
	v_mov_b32_e32 v62, v160
	v_mov_b32_e32 v63, v160
	s_waitcnt vmcnt(22)
	v_mov_b32_e32 v64, v160
	v_mov_b32_e32 v65, v160
	v_mov_b32_e32 v66, v160
	v_mov_b32_e32 v67, v160
	v_mov_b32_e32 v68, v160
	v_mov_b32_e32 v69, v160
	v_mov_b32_e32 v70, v160
	v_mov_b32_e32 v71, v160
	v_mov_b32_e32 v80, v160
	v_mov_b32_e32 v81, v160
	v_mov_b32_e32 v82, v160
	v_mov_b32_e32 v83, v160
	s_waitcnt vmcnt(21)
	v_mov_b32_e32 v84, v160
	v_mov_b32_e32 v85, v160
	v_mov_b32_e32 v86, v160
	v_mov_b32_e32 v87, v160
	s_waitcnt vmcnt(20)
	v_mov_b32_e32 v88, v160
	v_mov_b32_e32 v89, v160
	v_mov_b32_e32 v90, v160
	v_mov_b32_e32 v91, v160
	v_mov_b32_e32 v92, v160
	v_mov_b32_e32 v93, v160
	v_mov_b32_e32 v94, v160
	v_mov_b32_e32 v95, v160
	v_mov_b32_e32 v96, v160
	v_mov_b32_e32 v97, v160
	v_mov_b32_e32 v98, v160
	v_mov_b32_e32 v99, v160
	v_mov_b32_e32 v100, v160
	v_mov_b32_e32 v101, v160
	v_mov_b32_e32 v102, v160
	v_mov_b32_e32 v103, v160
	v_mov_b32_e32 v104, v160
	v_mov_b32_e32 v105, v160
	v_mov_b32_e32 v106, v160
	v_mov_b32_e32 v107, v160
	v_mov_b32_e32 v108, v160
	v_mov_b32_e32 v109, v160
	v_mov_b32_e32 v110, v160
	v_mov_b32_e32 v111, v160
	v_mov_b32_e32 v112, v160
	v_mov_b32_e32 v113, v160
	v_mov_b32_e32 v114, v160
	v_mov_b32_e32 v115, v160
	v_mov_b32_e32 v116, v160
	v_mov_b32_e32 v117, v160
	v_mov_b32_e32 v118, v160
	v_mov_b32_e32 v119, v160
	v_mov_b32_e32 v120, v160
	v_mov_b32_e32 v121, v160
	v_mov_b32_e32 v122, v160
	v_mov_b32_e32 v123, v160
	v_mov_b32_e32 v124, v160
	v_mov_b32_e32 v125, v160
	v_mov_b32_e32 v126, v160
	v_mov_b32_e32 v127, v160
	v_mov_b32_e32 v128, v160
	v_mov_b32_e32 v129, v160
	v_mov_b32_e32 v130, v160
	v_mov_b32_e32 v131, v160
	v_mov_b32_e32 v132, v160
	v_mov_b32_e32 v133, v160
	v_mov_b32_e32 v134, v160
	v_mov_b32_e32 v135, v160
	v_mov_b32_e32 v140, v160
	v_mov_b32_e32 v141, v160
	v_mov_b32_e32 v142, v160
	v_mov_b32_e32 v143, v160
	v_mov_b32_e32 v148, v160
	v_mov_b32_e32 v149, v160
	v_mov_b32_e32 v150, v160
	v_mov_b32_e32 v151, v160
	s_mov_b32 s7, 0x284000
	s_mov_b32 s25, 0x294000
; template <int MI, bool SWAP, bool F8 = false>
; __device__ __forceinline__ void gemm_core(const bf16_t* __restrict__ A, int lda, const bf16_t* __restrict__ B, int ldb,
;                                           int K, char* smem, f32x4 (&acc)[MI][4]) {
;     ...
;   for (int kt = 0; kt < nk; ++kt) {
;     __syncthreads();
; #pragma unroll
;     for (int i = 0; i < MI; ++i) *(u32x4*)(smem + woff + i * 4096) = ra[i];
; #pragma unroll
;     for (int i = 0; i < 4; ++i) *(u32x4*)(smem + 32768 + woff + i * 4096) = rb[i];
;     __syncthreads();
;     if (kt + 1 < nk) {
; #pragma unroll
;       for (int i = 0; i < MI; ++i) ra[i] = *(const u32x4*)(ap + (size_t)(32 * i) * lda + (kt + 1) * 64);
; #pragma unroll
;       for (int i = 0; i < 4; ++i) rb[i] = *(const u32x4*)(bp + (size_t)(32 * i) * ldb + (kt + 1) * 64);
;     }
;     if (F8) {
;       const int c0 = (g ^ (li & 7)) << 4, c1 = ((4 + g) ^ (li & 7)) << 4;
;       i32x8 wf8[4];
; #pragma unroll
;       for (int j = 0; j < 4; ++j) {
;         const char* rp = smem + wrow + ((j & 1) * 16 + (j >> 1) * 64) * 128;
;         const u32x4 lo = *(const u32x4*)(rp + c0), hi = *(const u32x4*)(rp + c1);
;         wf8[j] = (i32x8){(int)lo.x, (int)lo.y, (int)lo.z, (int)lo.w, (int)hi.x, (int)hi.y, (int)hi.z, (int)hi.w};
;       }
; #pragma unroll
;       for (int i = 0; i < MI; ++i) {
;         const char* rp = smem + xrow + i * 2048;
;         const u32x4 lo = *(const u32x4*)(rp + c0), hi = *(const u32x4*)(rp + c1);
;         const i32x8 xf8 = {(int)lo.x, (int)lo.y, (int)lo.z, (int)lo.w, (int)hi.x, (int)hi.y, (int)hi.z, (int)hi.w};
; #pragma unroll
;         for (int j = 0; j < 4; ++j)
;           acc[i][j] = __builtin_amdgcn_mfma_scale_f32_16x16x128_f8f6f4(wf8[j], xf8, acc[i][j], 0, 0, 0, 0x77777777, 0, 0x7f7f7f7f);
;       }
;     } else {
; #pragma unroll
;     for (int kk = 0; kk < 2; ++kk) {
;       const int ch = ((kk * 4 + g) ^ (li & 7)) << 4;
;       bf16x8 xf[MI], wf[4];
; #pragma unroll
;       for (int j = 0; j < 4; ++j) wf[j] = *(const bf16x8*)(smem + wrow + ((j & 1) * 16 + (j >> 1) * 64) * 128 + ch);
; #pragma unroll
;       for (int i = 0; i < MI; ++i) xf[i] = *(const bf16x8*)(smem + xrow + i * 2048 + ch);
; #pragma unroll
;       for (int i = 0; i < MI; ++i)
; #pragma unroll
;         for (int j = 0; j < 4; ++j) {
.LBB0_301:
	v_add_u32_e32 v213, v204, v205
	s_barrier
	s_mov_b32 m0, s62
	s_nop 0
	global_load_lds_dwordx4 v252, s[56:57]
	s_add_u32 m0, s62, 0x1000
	s_nop 0
	global_load_lds_dwordx4 v253, s[56:57]
	s_add_u32 s56, s56, 0x20000
	s_addc_u32 s57, s57, 0
	s_add_u32 m0, s62, 0x2000
	s_nop 0
	global_load_lds_dwordx4 v252, s[56:57]
	s_add_u32 m0, s62, 0x3000
	s_nop 0
	global_load_lds_dwordx4 v253, s[56:57]
	s_add_u32 s56, s56, 0x20000
	s_addc_u32 s57, s57, 0
	s_add_u32 m0, s62, 0x4000
	s_nop 0
	global_load_lds_dwordx4 v252, s[56:57]
	s_add_u32 m0, s62, 0x5000
	s_nop 0
	global_load_lds_dwordx4 v253, s[56:57]
	s_add_u32 s56, s56, 0x20000
	s_addc_u32 s57, s57, 0
	s_add_u32 m0, s62, 0x6000
	s_nop 0
	global_load_lds_dwordx4 v252, s[56:57]
	s_add_u32 m0, s62, 0x7000
	s_nop 0
	global_load_lds_dwordx4 v253, s[56:57]
	s_sub_u32 s56, s56, 0x60000
	s_subb_u32 s57, s57, 0
	s_add_u32 m0, s62, 0x8000
	s_nop 0
	global_load_lds_dwordx4 v252, s[58:59]
	s_add_u32 m0, s62, 0x9000
	s_nop 0
	global_load_lds_dwordx4 v253, s[58:59]
	s_add_u32 s58, s58, 0x20000
	s_addc_u32 s59, s59, 0
	s_add_u32 m0, s62, 0xa000
	s_nop 0
	global_load_lds_dwordx4 v252, s[58:59]
	s_add_u32 m0, s62, 0xb000
	s_nop 0
	global_load_lds_dwordx4 v253, s[58:59]
	s_sub_u32 s58, s58, 0x20000
	s_subb_u32 s59, s59, 0
	v_add_u32_e32 v252, 0x80, v252
	v_add_u32_e32 v253, 0x80, v253
	global_load_dword v223, v222, s[56:57] offset:256
	v_add_u32_e32 v222, 0x80, v222
	s_waitcnt vmcnt(1)
	s_barrier
	v_add_u32_e32 v0, v203, v205
	ds_read_b128 v[136:139], v213 offset:32768
	ds_read_b128 v[144:147], v213 offset:34816
	ds_read_b128 v[152:155], v0
	ds_read_b128 v[156:159], v0 offset:2048
	ds_read_b128 v[164:167], v213 offset:40960
	ds_read_b128 v[168:171], v213 offset:43008
	s_waitcnt lgkmcnt(3)
	v_mfma_f32_16x16x32_bf16 v[148:151], v[136:139], v[152:155], v[148:151]
	v_add_u32_e32 v215, v204, v206
	v_add_u32_e32 v207, v203, v206
	v_mfma_f32_16x16x32_bf16 v[140:143], v[144:147], v[152:155], v[140:143]
	s_waitcnt lgkmcnt(1)
	v_mfma_f32_16x16x32_bf16 v[132:135], v[164:167], v[152:155], v[132:135]
	s_waitcnt lgkmcnt(0)
	v_mfma_f32_16x16x32_bf16 v[128:131], v[168:171], v[152:155], v[128:131]
	v_mfma_f32_16x16x32_bf16 v[124:127], v[136:139], v[156:159], v[124:127]
	v_mfma_f32_16x16x32_bf16 v[120:123], v[144:147], v[156:159], v[120:123]
	v_mfma_f32_16x16x32_bf16 v[116:119], v[164:167], v[156:159], v[116:119]
	v_mfma_f32_16x16x32_bf16 v[112:115], v[168:171], v[156:159], v[112:115]
	ds_read_b128 v[152:155], v0 offset:4096
	ds_read_b128 v[156:159], v0 offset:6144
	s_waitcnt lgkmcnt(1)
	v_mfma_f32_16x16x32_bf16 v[108:111], v[136:139], v[152:155], v[108:111]
	v_mfma_f32_16x16x32_bf16 v[104:107], v[144:147], v[152:155], v[104:107]
	v_mfma_f32_16x16x32_bf16 v[100:103], v[164:167], v[152:155], v[100:103]
	v_mfma_f32_16x16x32_bf16 v[96:99], v[168:171], v[152:155], v[96:99]
	s_waitcnt lgkmcnt(0)
	v_mfma_f32_16x16x32_bf16 v[92:95], v[136:139], v[156:159], v[92:95]
	v_mfma_f32_16x16x32_bf16 v[88:91], v[144:147], v[156:159], v[88:91]
	v_mfma_f32_16x16x32_bf16 v[84:87], v[164:167], v[156:159], v[84:87]
	v_mfma_f32_16x16x32_bf16 v[80:83], v[168:171], v[156:159], v[80:83]
	ds_read_b128 v[152:155], v0 offset:8192
	ds_read_b128 v[156:159], v0 offset:10240
	s_waitcnt lgkmcnt(1)
	v_mfma_f32_16x16x32_bf16 v[68:71], v[136:139], v[152:155], v[68:71]
	v_mfma_f32_16x16x32_bf16 v[64:67], v[144:147], v[152:155], v[64:67]
	v_mfma_f32_16x16x32_bf16 v[60:63], v[164:167], v[152:155], v[60:63]
	v_mfma_f32_16x16x32_bf16 v[56:59], v[168:171], v[152:155], v[56:59]
	s_waitcnt lgkmcnt(0)
	v_mfma_f32_16x16x32_bf16 v[48:51], v[136:139], v[156:159], v[48:51]
	v_mfma_f32_16x16x32_bf16 v[44:47], v[144:147], v[156:159], v[44:47]
	v_mfma_f32_16x16x32_bf16 v[40:43], v[164:167], v[156:159], v[40:43]
	v_mfma_f32_16x16x32_bf16 v[36:39], v[168:171], v[156:159], v[36:39]
	ds_read_b128 v[152:155], v0 offset:12288
	ds_read_b128 v[156:159], v0 offset:14336
	ds_read_b128 v[172:175], v215 offset:32768
	ds_read_b128 v[180:183], v215 offset:34816
	s_waitcnt lgkmcnt(3)
	v_mfma_f32_16x16x32_bf16 v[28:31], v[136:139], v[152:155], v[28:31]
	v_mfma_f32_16x16x32_bf16 v[24:27], v[144:147], v[152:155], v[24:27]
	v_mfma_f32_16x16x32_bf16 v[76:79], v[164:167], v[152:155], v[76:79]
	v_mfma_f32_16x16x32_bf16 v[72:75], v[168:171], v[152:155], v[72:75]
	s_waitcnt lgkmcnt(2)
	v_mfma_f32_16x16x32_bf16 v[52:55], v[136:139], v[156:159], v[52:55]
	v_mfma_f32_16x16x32_bf16 v[32:35], v[144:147], v[156:159], v[32:35]
	ds_read_b128 v[136:139], v207
	ds_read_b128 v[144:147], v207 offset:2048
	ds_read_b128 v[192:195], v215 offset:40960
	ds_read_b128 v[196:199], v215 offset:43008
	v_mfma_f32_16x16x32_bf16 v[20:23], v[164:167], v[156:159], v[20:23]
	v_mfma_f32_16x16x32_bf16 v[160:163], v[168:171], v[156:159], v[160:163]
	s_waitcnt lgkmcnt(3)
	v_mfma_f32_16x16x32_bf16 v[148:151], v[172:175], v[136:139], v[148:151]
	v_mfma_f32_16x16x32_bf16 v[140:143], v[180:183], v[136:139], v[140:143]
	s_waitcnt lgkmcnt(1)
	v_mfma_f32_16x16x32_bf16 v[132:135], v[192:195], v[136:139], v[132:135]
	s_waitcnt lgkmcnt(0)
	v_mfma_f32_16x16x32_bf16 v[128:131], v[196:199], v[136:139], v[128:131]
	v_mfma_f32_16x16x32_bf16 v[124:127], v[172:175], v[144:147], v[124:127]
	v_mfma_f32_16x16x32_bf16 v[120:123], v[180:183], v[144:147], v[120:123]
	v_mfma_f32_16x16x32_bf16 v[116:119], v[192:195], v[144:147], v[116:119]
	v_mfma_f32_16x16x32_bf16 v[112:115], v[196:199], v[144:147], v[112:115]
	ds_read_b128 v[136:139], v207 offset:4096
	ds_read_b128 v[144:147], v207 offset:6144
	s_waitcnt lgkmcnt(1)
; template <int MI, bool SWAP, bool F8 = false>
; __device__ __forceinline__ void gemm_core(const bf16_t* __restrict__ A, int lda, const bf16_t* __restrict__ B, int ldb,
;                                           int K, char* smem, f32x4 (&acc)[MI][4]) {
;     ...
;   for (int kt = 0; kt < nk; ++kt) {
;     __syncthreads();
; #pragma unroll
;     for (int i = 0; i < MI; ++i) *(u32x4*)(smem + woff + i * 4096) = ra[i];
; #pragma unroll
;     for (int i = 0; i < 4; ++i) *(u32x4*)(smem + 32768 + woff + i * 4096) = rb[i];
;     __syncthreads();
;     if (kt + 1 < nk) {
; #pragma unroll
;       for (int i = 0; i < MI; ++i) ra[i] = *(const u32x4*)(ap + (size_t)(32 * i) * lda + (kt + 1) * 64);
; #pragma unroll
;       for (int i = 0; i < 4; ++i) rb[i] = *(const u32x4*)(bp + (size_t)(32 * i) * ldb + (kt + 1) * 64);
;     }
;     if (F8) {
;       const int c0 = (g ^ (li & 7)) << 4, c1 = ((4 + g) ^ (li & 7)) << 4;
;       i32x8 wf8[4];
; #pragma unroll
;       for (int j = 0; j < 4; ++j) {
;         const char* rp = smem + wrow + ((j & 1) * 16 + (j >> 1) * 64) * 128;
;         const u32x4 lo = *(const u32x4*)(rp + c0), hi = *(const u32x4*)(rp + c1);
;         wf8[j] = (i32x8){(int)lo.x, (int)lo.y, (int)lo.z, (int)lo.w, (int)hi.x, (int)hi.y, (int)hi.z, (int)hi.w};
;       }
; #pragma unroll
;       for (int i = 0; i < MI; ++i) {
;         const char* rp = smem + xrow + i * 2048;
;         const u32x4 lo = *(const u32x4*)(rp + c0), hi = *(const u32x4*)(rp + c1);
;         const i32x8 xf8 = {(int)lo.x, (int)lo.y, (int)lo.z, (int)lo.w, (int)hi.x, (int)hi.y, (int)hi.z, (int)hi.w};
; #pragma unroll
;         for (int j = 0; j < 4; ++j)
;           acc[i][j] = __builtin_amdgcn_mfma_scale_f32_16x16x128_f8f6f4(wf8[j], xf8, acc[i][j], 0, 0, 0, 0x77777777, 0, 0x7f7f7f7f);
;       }
;     } else {
; #pragma unroll
;     for (int kk = 0; kk < 2; ++kk) {
;       const int ch = ((kk * 4 + g) ^ (li & 7)) << 4;
;       bf16x8 xf[MI], wf[4];
; #pragma unroll
;       for (int j = 0; j < 4; ++j) wf[j] = *(const bf16x8*)(smem + wrow + ((j & 1) * 16 + (j >> 1) * 64) * 128 + ch);
; #pragma unroll
;       for (int i = 0; i < MI; ++i) xf[i] = *(const bf16x8*)(smem + xrow + i * 2048 + ch);
; #pragma unroll
;       for (int i = 0; i < MI; ++i)
; #pragma unroll
;         for (int j = 0; j < 4; ++j) {
	v_mfma_f32_16x16x32_bf16 v[108:111], v[172:175], v[136:139], v[108:111]
	ds_read_b128 v[152:155], v207 offset:12288
	ds_read_b128 v[216:219], v207 offset:14336
	v_mfma_f32_16x16x32_bf16 v[104:107], v[180:183], v[136:139], v[104:107]
	v_mfma_f32_16x16x32_bf16 v[100:103], v[192:195], v[136:139], v[100:103]
	v_mfma_f32_16x16x32_bf16 v[96:99], v[196:199], v[136:139], v[96:99]
	ds_read_b128 v[136:139], v207 offset:8192
	s_waitcnt lgkmcnt(3)
	v_mfma_f32_16x16x32_bf16 v[92:95], v[172:175], v[144:147], v[92:95]
	v_mfma_f32_16x16x32_bf16 v[88:91], v[180:183], v[144:147], v[88:91]
	v_mfma_f32_16x16x32_bf16 v[84:87], v[192:195], v[144:147], v[84:87]
	v_mfma_f32_16x16x32_bf16 v[80:83], v[196:199], v[144:147], v[80:83]
	ds_read_b128 v[144:147], v207 offset:10240
	s_waitcnt lgkmcnt(1)
	v_mfma_f32_16x16x32_bf16 v[68:71], v[172:175], v[136:139], v[68:71]
	v_mfma_f32_16x16x32_bf16 v[64:67], v[180:183], v[136:139], v[64:67]
	v_mfma_f32_16x16x32_bf16 v[60:63], v[192:195], v[136:139], v[60:63]
	v_mfma_f32_16x16x32_bf16 v[56:59], v[196:199], v[136:139], v[56:59]
	s_waitcnt lgkmcnt(0)
	v_mfma_f32_16x16x32_bf16 v[48:51], v[172:175], v[144:147], v[48:51]
	v_mfma_f32_16x16x32_bf16 v[44:47], v[180:183], v[144:147], v[44:47]
	v_mfma_f32_16x16x32_bf16 v[40:43], v[192:195], v[144:147], v[40:43]
	v_mfma_f32_16x16x32_bf16 v[36:39], v[196:199], v[144:147], v[36:39]
	v_mfma_f32_16x16x32_bf16 v[28:31], v[172:175], v[152:155], v[28:31]
	v_mfma_f32_16x16x32_bf16 v[24:27], v[180:183], v[152:155], v[24:27]
	v_mfma_f32_16x16x32_bf16 v[76:79], v[192:195], v[152:155], v[76:79]
	v_mfma_f32_16x16x32_bf16 v[72:75], v[196:199], v[152:155], v[72:75]
	v_mfma_f32_16x16x32_bf16 v[52:55], v[172:175], v[216:219], v[52:55]
	v_mfma_f32_16x16x32_bf16 v[32:35], v[180:183], v[216:219], v[32:35]
	v_mfma_f32_16x16x32_bf16 v[20:23], v[192:195], v[216:219], v[20:23]
	v_mfma_f32_16x16x32_bf16 v[160:163], v[196:199], v[216:219], v[160:163]
	s_add_u32 s26, s26, 0x80
	s_addc_u32 s27, s27, 0
	s_cmpk_lg_i32 s26, 0x780
	s_cbranch_scc1 .LBB0_301
	s_barrier
	s_mov_b32 m0, s62
	s_nop 0
	global_load_lds_dwordx4 v252, s[56:57]
	s_add_u32 m0, s62, 0x1000
	s_nop 0
	global_load_lds_dwordx4 v253, s[56:57]
	s_add_u32 s56, s56, 0x20000
	s_addc_u32 s57, s57, 0
	s_add_u32 m0, s62, 0x2000
	s_nop 0
	global_load_lds_dwordx4 v252, s[56:57]
	s_add_u32 m0, s62, 0x3000
	s_nop 0
	global_load_lds_dwordx4 v253, s[56:57]
	s_add_u32 s56, s56, 0x20000
	s_addc_u32 s57, s57, 0
	s_add_u32 m0, s62, 0x4000
	s_nop 0
	global_load_lds_dwordx4 v252, s[56:57]
	s_add_u32 m0, s62, 0x5000
	s_nop 0
	global_load_lds_dwordx4 v253, s[56:57]
	s_add_u32 s56, s56, 0x20000
	s_addc_u32 s57, s57, 0
	s_add_u32 m0, s62, 0x6000
	s_nop 0
	global_load_lds_dwordx4 v252, s[56:57]
	s_add_u32 m0, s62, 0x7000
	s_nop 0
	global_load_lds_dwordx4 v253, s[56:57]
	s_sub_u32 s56, s56, 0x60000
	s_subb_u32 s57, s57, 0
	s_add_u32 m0, s62, 0x8000
	s_nop 0
	global_load_lds_dwordx4 v252, s[58:59]
	s_add_u32 m0, s62, 0x9000
	s_nop 0
	global_load_lds_dwordx4 v253, s[58:59]
	s_add_u32 s58, s58, 0x20000
	s_addc_u32 s59, s59, 0
	s_add_u32 m0, s62, 0xa000
	s_nop 0
	global_load_lds_dwordx4 v252, s[58:59]
	s_add_u32 m0, s62, 0xb000
	s_nop 0
	global_load_lds_dwordx4 v253, s[58:59]
	s_sub_u32 s58, s58, 0x20000
	s_subb_u32 s59, s59, 0
	s_waitcnt vmcnt(0)
	s_barrier
	v_bfe_u32 v12, v208, 4, 1
	v_mul_u32_u24_e32 v12, 24, v12
	v_mov_b32_e32 v13, 0
	ds_read_b128 v[136:139], v213 offset:32768
	ds_read_b128 v[144:147], v213 offset:34816
	ds_read_b128 v[152:155], v0
	ds_read_b128 v[156:159], v0 offset:2048
	ds_read_b128 v[164:167], v213 offset:40960
	ds_read_b128 v[168:171], v213 offset:43008
	s_waitcnt lgkmcnt(3)
	v_mfma_f32_16x16x32_bf16 v[148:151], v[136:139], v[152:155], v[148:151]
	s_cmp_eq_u32 s42, 6
	s_cselect_b64 s[26:27], -1, 0
	s_cmp_lg_u32 s42, 6
	v_mfma_f32_16x16x32_bf16 v[140:143], v[144:147], v[152:155], v[140:143]
	s_cselect_b64 s[30:31], -1, 0
	s_and_b64 vcc, exec, s[26:27]
	s_waitcnt lgkmcnt(1)
	v_mfma_f32_16x16x32_bf16 v[132:135], v[164:167], v[152:155], v[132:135]
	s_waitcnt lgkmcnt(0)
	v_mfma_f32_16x16x32_bf16 v[128:131], v[168:171], v[152:155], v[128:131]
	v_mfma_f32_16x16x32_bf16 v[172:175], v[136:139], v[156:159], v[124:127]
	s_nop 2
	ds_read_b128 v[124:127], v0 offset:4096
	ds_read_b128 v[152:155], v0 offset:6144
	s_waitcnt lgkmcnt(0)
	v_mfma_f32_16x16x32_bf16 v[176:179], v[164:167], v[152:155], v[84:87]
	v_mfma_f32_16x16x32_bf16 v[180:183], v[168:171], v[152:155], v[80:83]
	s_nop 2
	ds_read_b128 v[80:83], v0 offset:8192
	ds_read_b128 v[84:87], v0 offset:10240
	s_waitcnt lgkmcnt(1)
	v_mfma_f32_16x16x32_bf16 v[196:199], v[168:171], v[80:83], v[56:59]
	s_waitcnt lgkmcnt(0)
	v_mfma_f32_16x16x32_bf16 v[200:203], v[136:139], v[84:87], v[48:51]
	s_nop 2
	ds_read_b128 v[48:51], v0 offset:12288
	ds_read_b128 v[56:59], v0 offset:14336
	v_mfma_f32_16x16x32_bf16 v[116:119], v[164:167], v[156:159], v[116:119]
	v_mfma_f32_16x16x32_bf16 v[112:115], v[168:171], v[156:159], v[112:115]
	v_mfma_f32_16x16x32_bf16 v[100:103], v[164:167], v[124:127], v[100:103]
	v_mfma_f32_16x16x32_bf16 v[96:99], v[168:171], v[124:127], v[96:99]
	v_mfma_f32_16x16x32_bf16 v[192:195], v[164:167], v[80:83], v[60:63]
	v_mfma_f32_16x16x32_bf16 v[40:43], v[164:167], v[84:87], v[40:43]
	v_mfma_f32_16x16x32_bf16 v[36:39], v[168:171], v[84:87], v[36:39]
	s_waitcnt lgkmcnt(1)
	v_mfma_f32_16x16x32_bf16 v[28:31], v[136:139], v[48:51], v[28:31]
	v_mfma_f32_16x16x32_bf16 v[24:27], v[144:147], v[48:51], v[24:27]
	v_mfma_f32_16x16x32_bf16 v[76:79], v[164:167], v[48:51], v[76:79]
	v_mfma_f32_16x16x32_bf16 v[216:219], v[168:171], v[48:51], v[72:75]
	s_waitcnt lgkmcnt(0)
; template <int MI, bool SWAP, bool F8 = false>
; __device__ __forceinline__ void gemm_core(const bf16_t* __restrict__ A, int lda, const bf16_t* __restrict__ B, int ldb,
;                                           int K, char* smem, f32x4 (&acc)[MI][4]) {
;     ...
;     for (int kk = 0; kk < 2; ++kk) {
;       const int ch = ((kk * 4 + g) ^ (li & 7)) << 4;
;       bf16x8 xf[MI], wf[4];
; #pragma unroll
;       for (int j = 0; j < 4; ++j) wf[j] = *(const bf16x8*)(smem + wrow + ((j & 1) * 16 + (j >> 1) * 64) * 128 + ch);
; #pragma unroll
;       for (int i = 0; i < MI; ++i) xf[i] = *(const bf16x8*)(smem + xrow + i * 2048 + ch);
; #pragma unroll
;       for (int i = 0; i < MI; ++i)
; #pragma unroll
;         for (int j = 0; j < 4; ++j) {
;           if (SWAP) acc[i][j] = __builtin_amdgcn_mfma_f32_16x16x32_bf16(xf[i], wf[j], acc[i][j], 0, 0, 0);
;           else acc[i][j] = __builtin_amdgcn_mfma_f32_16x16x32_bf16(wf[j], xf[i], acc[i][j], 0, 0, 0);
;         }
; __device__ void even_in_tile(const P& p, int li_even, int tm, int tn, char* smem) {
;     ...
;   if (seg != 6) {
;     const float* ctab = (const float*)(ws + OFF_COS);
;     const float* stab = (const float*)(ws + OFF_SIN);
; #pragma unroll
;     for (int i = 0; i < MI; ++i) {
;       const int s = s0 + MROW(i);
; #pragma unroll
;       for (int jj = 0; jj < 2; ++jj) {
;         const int d = wn * 32 + jj * 16 + g * 4;
;         const f32x4 c = *(const f32x4*)(ctab + s * 64 + d);
;         const f32x4 sn = *(const f32x4*)(stab + s * 64 + d);
	v_mfma_f32_16x16x32_bf16 v[224:227], v[144:147], v[56:59], v[32:35]
	v_mfma_f32_16x16x32_bf16 v[20:23], v[164:167], v[56:59], v[20:23]
	ds_read_b128 v[164:167], v215 offset:32768
	v_mfma_f32_16x16x32_bf16 v[160:163], v[168:171], v[56:59], v[160:163]
	ds_read_b128 v[168:171], v215 offset:34816
	ds_read_b128 v[32:35], v207
	ds_read_b128 v[48:51], v207 offset:2048
	ds_read_b128 v[228:231], v215 offset:40960
	ds_read_b128 v[232:235], v215 offset:43008
	v_mfma_f32_16x16x32_bf16 v[120:123], v[144:147], v[156:159], v[120:123]
	v_mov_b32_e32 v215, v208
	v_mfma_f32_16x16x32_bf16 v[108:111], v[136:139], v[124:127], v[108:111]
	v_mfma_f32_16x16x32_bf16 v[104:107], v[144:147], v[124:127], v[104:107]
	v_mfma_f32_16x16x32_bf16 v[92:95], v[136:139], v[152:155], v[92:95]
	v_mfma_f32_16x16x32_bf16 v[156:159], v[144:147], v[152:155], v[88:91]
	v_mfma_f32_16x16x32_bf16 v[184:187], v[136:139], v[80:83], v[68:71]
	v_mfma_f32_16x16x32_bf16 v[188:191], v[144:147], v[80:83], v[64:67]
	v_mfma_f32_16x16x32_bf16 v[44:47], v[144:147], v[84:87], v[44:47]
	v_mfma_f32_16x16x32_bf16 v[220:223], v[136:139], v[56:59], v[52:55]
	s_waitcnt lgkmcnt(3)
	v_mfma_f32_16x16x32_bf16 v[124:127], v[164:167], v[32:35], v[148:151]
	v_mfma_f32_16x16x32_bf16 v[150:153], v[168:171], v[32:35], v[140:143]
	s_waitcnt lgkmcnt(1)
	v_mfma_f32_16x16x32_bf16 v[88:91], v[228:231], v[32:35], v[132:135]
	s_waitcnt lgkmcnt(0)
	v_mfma_f32_16x16x32_bf16 v[84:87], v[232:235], v[32:35], v[128:131]
	v_mfma_f32_16x16x32_bf16 v[134:137], v[164:167], v[48:51], v[172:175]
	v_mfma_f32_16x16x32_bf16 v[138:141], v[168:171], v[48:51], v[120:123]
	v_mfma_f32_16x16x32_bf16 v[80:83], v[228:231], v[48:51], v[116:119]
	v_mfma_f32_16x16x32_bf16 v[72:75], v[232:235], v[48:51], v[112:115]
	ds_read_b128 v[32:35], v207 offset:4096
	ds_read_b128 v[48:51], v207 offset:6144
	s_waitcnt lgkmcnt(1)
	v_mfma_f32_16x16x32_bf16 v[142:145], v[164:167], v[32:35], v[108:111]
	v_mfma_f32_16x16x32_bf16 v[146:149], v[168:171], v[32:35], v[104:107]
	v_mfma_f32_16x16x32_bf16 v[68:71], v[228:231], v[32:35], v[100:103]
	v_mfma_f32_16x16x32_bf16 v[64:67], v[232:235], v[32:35], v[96:99]
	s_waitcnt lgkmcnt(0)
	v_mfma_f32_16x16x32_bf16 v[128:131], v[164:167], v[48:51], v[92:95]
	ds_read_b128 v[32:35], v207 offset:8192
	s_nop 1
	ds_read_b128 v[92:95], v207 offset:10240
	v_mfma_f32_16x16x32_bf16 v[120:123], v[168:171], v[48:51], v[156:159]
	v_mfma_f32_16x16x32_bf16 v[60:63], v[228:231], v[48:51], v[176:179]
	v_mfma_f32_16x16x32_bf16 v[56:59], v[232:235], v[48:51], v[180:183]
	s_waitcnt lgkmcnt(1)
	v_mfma_f32_16x16x32_bf16 v[112:115], v[164:167], v[32:35], v[184:187]
	v_mfma_f32_16x16x32_bf16 v[108:111], v[168:171], v[32:35], v[188:191]
	v_mfma_f32_16x16x32_bf16 v[52:55], v[228:231], v[32:35], v[192:195]
	v_mfma_f32_16x16x32_bf16 v[48:51], v[232:235], v[32:35], v[196:199]
	ds_read_b128 v[32:35], v207 offset:12288
	ds_read_b128 v[116:119], v207 offset:14336
	s_waitcnt lgkmcnt(2)
	v_mfma_f32_16x16x32_bf16 v[104:107], v[164:167], v[92:95], v[200:203]
	v_and_b32_e32 v213, 15, v215
	v_mfma_f32_16x16x32_bf16 v[100:103], v[168:171], v[92:95], v[44:47]
	v_mfma_f32_16x16x32_bf16 v[44:47], v[228:231], v[92:95], v[40:43]
	v_mfma_f32_16x16x32_bf16 v[40:43], v[232:235], v[92:95], v[36:39]
	s_waitcnt lgkmcnt(1)
	v_mfma_f32_16x16x32_bf16 v[96:99], v[164:167], v[32:35], v[28:31]
	v_mfma_f32_16x16x32_bf16 v[92:95], v[168:171], v[32:35], v[24:27]
	v_mfma_f32_16x16x32_bf16 v[36:39], v[228:231], v[32:35], v[76:79]
	v_mfma_f32_16x16x32_bf16 v[32:35], v[232:235], v[32:35], v[216:219]
	s_waitcnt lgkmcnt(0)
	v_mfma_f32_16x16x32_bf16 v[76:79], v[164:167], v[116:119], v[220:223]
	s_nop 0
	v_bfe_u32 v218, v215, 6, 1
	v_bfe_u32 v219, v215, 4, 2
	v_mfma_f32_16x16x32_bf16 v[28:31], v[168:171], v[116:119], v[224:227]
	v_mfma_f32_16x16x32_bf16 v[24:27], v[228:231], v[116:119], v[20:23]
	v_mfma_f32_16x16x32_bf16 v[20:23], v[232:235], v[116:119], v[160:163]
	s_cbranch_vccnz .LBB0_315
	v_and_b32_e32 v0, 0x3ffff80, v215
	v_add_u32_e32 v0, s41, v0
	s_add_u32 s34, s45, 0x4000
	v_or_b32_e32 v0, v0, v213
	s_addc_u32 s35, s48, 0
	v_lshlrev_b32_e32 v2, 6, v0
	s_add_u32 s36, s45, 0x104000
	v_ashrrev_i32_e32 v3, 31, v2
	s_addc_u32 s37, s48, 0
	v_lshlrev_b64 v[116:117], 2, v[2:3]
	v_lshlrev_b32_e32 v0, 4, v219
	v_lshl_add_u64 v[118:119], s[34:35], 0, v[116:117]
	v_lshl_add_u64 v[116:117], s[36:37], 0, v[116:117]
	v_lshl_or_b32 v0, v218, 7, v0
	v_lshl_add_u64 v[132:133], v[118:119], 0, v[0:1]
	v_lshl_add_u64 v[162:163], v[116:117], 0, v[0:1]
	v_lshl_add_u32 v236, v2, 2, v0
	global_load_dwordx4 v[164:167], v236, s[34:35]
	global_load_dwordx4 v[168:171], v236, s[36:37]
	global_load_dwordx4 v[172:175], v236, s[34:35] offset:64
	global_load_dwordx4 v[176:179], v236, s[36:37] offset:64
	v_add_u32_e32 v236, 0x1000, v236
	global_load_dwordx4 v[180:183], v236, s[34:35]
	global_load_dwordx4 v[184:187], v236, s[36:37]
	global_load_dwordx4 v[188:191], v236, s[34:35] offset:64
	global_load_dwordx4 v[192:195], v236, s[36:37] offset:64
	v_add_u32_e32 v236, 0x1000, v236
	global_load_dwordx4 v[196:199], v236, s[34:35]
	global_load_dwordx4 v[200:203], v236, s[36:37]
	global_load_dwordx4 v[204:207], v236, s[34:35] offset:64
	global_load_dwordx4 v[220:223], v236, s[36:37] offset:64
	v_add_u32_e32 v236, 0x1000, v236
	global_load_dwordx4 v[224:227], v236, s[34:35]
	global_load_dwordx4 v[228:231], v236, s[36:37]
	global_load_dwordx4 v[232:235], v236, s[34:35] offset:64
	global_load_dwordx4 v[4:7], v236, s[36:37] offset:64
	v_add_u32_e32 v236, 0x1000, v236
	s_waitcnt vmcnt(14)
; __device__ void even_in_tile(const P& p, int li_even, int tm, int tn, char* smem) {
;     ...
; #pragma unroll
;     for (int i = 0; i < MI; ++i) {
;       const int s = s0 + MROW(i);
; #pragma unroll
;       for (int jj = 0; jj < 2; ++jj) {
;         const int d = wn * 32 + jj * 16 + g * 4;
;         const f32x4 c = *(const f32x4*)(ctab + s * 64 + d);
;         const f32x4 sn = *(const f32x4*)(stab + s * 64 + d);
; #pragma unroll
;         for (int r = 0; r < 4; ++r) {
;           const float a = acc[i][jj][r], bb = acc[i][jj + 2][r];
;           acc[i][jj][r] = a * c[r] - bb * sn[r];
;           acc[i][jj + 2][r] = bb * c[r] + a * sn[r];
;         }
;       }
;     }
;   }
	v_mov_b32_e32 v154, v164
	v_mov_b32_e32 v155, v165
	v_mov_b32_e32 v156, v166
	v_mov_b32_e32 v157, v167
	v_mov_b32_e32 v158, v168
	v_mov_b32_e32 v159, v169
	v_mov_b32_e32 v160, v170
	v_mov_b32_e32 v161, v171
	global_load_dwordx4 v[164:167], v236, s[34:35]
	global_load_dwordx4 v[168:171], v236, s[36:37]
	v_pk_mul_f32 v[116:117], v[88:89], v[158:159]
	v_pk_mul_f32 v[118:119], v[124:125], v[158:159]
	v_pk_fma_f32 v[116:117], v[124:125], v[154:155], v[116:117] neg_lo:[0,0,1] neg_hi:[0,0,1]
	v_pk_fma_f32 v[88:89], v[88:89], v[154:155], v[118:119]
	v_mul_f32_e32 v118, v126, v156
	v_mul_f32_e32 v124, v90, v160
	v_mul_f32_e32 v154, v90, v156
	v_mul_f32_e32 v156, v126, v160
	v_mov_b32_e32 v90, v127
	v_mov_b32_e32 v160, v157
	v_mov_b32_e32 v126, v91
	v_pk_mul_f32 v[158:159], v[90:91], v[160:161]
	v_pk_mul_f32 v[90:91], v[126:127], v[160:161]
	v_mov_b32_e32 v119, v158
	v_mov_b32_e32 v155, v90
	v_mov_b32_e32 v157, v91
	v_mov_b32_e32 v125, v159
	v_pk_add_f32 v[90:91], v[154:155], v[156:157]
	v_pk_add_f32 v[118:119], v[118:119], v[124:125] neg_lo:[0,1] neg_hi:[0,1]
	s_waitcnt vmcnt(14)
	v_mov_b32_e32 v154, v172
	v_mov_b32_e32 v155, v173
	v_mov_b32_e32 v156, v174
	v_mov_b32_e32 v157, v175
	v_mov_b32_e32 v158, v176
	v_mov_b32_e32 v159, v177
	v_mov_b32_e32 v160, v178
	v_mov_b32_e32 v161, v179
	global_load_dwordx4 v[172:175], v236, s[34:35] offset:64
	global_load_dwordx4 v[176:179], v236, s[36:37] offset:64
	v_add_u32_e32 v236, 0x1000, v236
	v_pk_mul_f32 v[124:125], v[84:85], v[158:159]
	v_pk_mul_f32 v[126:127], v[150:151], v[158:159]
	v_pk_fma_f32 v[124:125], v[150:151], v[154:155], v[124:125] neg_lo:[0,0,1] neg_hi:[0,0,1]
	v_pk_fma_f32 v[84:85], v[84:85], v[154:155], v[126:127]
	v_mul_f32_e32 v132, v86, v160
	v_mul_f32_e32 v150, v86, v156
	v_mul_f32_e32 v154, v152, v160
	v_mov_b32_e32 v86, v153
	v_mov_b32_e32 v160, v157
	v_mul_f32_e32 v126, v152, v156
	v_pk_mul_f32 v[156:157], v[86:87], v[160:161]
	v_mov_b32_e32 v152, v87
	v_mov_b32_e32 v127, v156
	v_mov_b32_e32 v133, v157
	v_pk_add_f32 v[126:127], v[126:127], v[132:133] neg_lo:[0,1] neg_hi:[0,1]
	v_or_b32_e32 v132, 0x400, v2
	v_pk_mul_f32 v[86:87], v[152:153], v[160:161]
	v_ashrrev_i32_e32 v133, 31, v132
	v_mov_b32_e32 v151, v86
	v_mov_b32_e32 v155, v87
	v_lshlrev_b64 v[132:133], 2, v[132:133]
	v_pk_add_f32 v[86:87], v[150:151], v[154:155]
	v_lshl_add_u64 v[150:151], s[34:35], 0, v[132:133]
	v_lshl_add_u64 v[132:133], s[36:37], 0, v[132:133]
	v_lshl_add_u64 v[158:159], v[150:151], 0, v[0:1]
	v_lshl_add_u64 v[160:161], v[132:133], 0, v[0:1]
	s_waitcnt vmcnt(14)
	v_mov_b32_e32 v150, v180
	v_mov_b32_e32 v151, v181
	v_mov_b32_e32 v152, v182
	v_mov_b32_e32 v153, v183
	v_mov_b32_e32 v154, v184
	v_mov_b32_e32 v155, v185
	v_mov_b32_e32 v156, v186
	v_mov_b32_e32 v157, v187
	global_load_dwordx4 v[180:183], v236, s[34:35]
	global_load_dwordx4 v[184:187], v236, s[36:37]
	v_pk_mul_f32 v[132:133], v[80:81], v[154:155]
	s_nop 0
	v_pk_fma_f32 v[132:133], v[134:135], v[150:151], v[132:133] neg_lo:[0,0,1] neg_hi:[0,0,1]
	v_pk_mul_f32 v[134:135], v[134:135], v[154:155]
	v_mul_f32_e32 v154, v136, v156
	v_pk_fma_f32 v[80:81], v[80:81], v[150:151], v[134:135]
	v_mul_f32_e32 v134, v136, v152
	v_mul_f32_e32 v150, v82, v156
	v_mul_f32_e32 v152, v82, v152
	v_mov_b32_e32 v82, v137
	v_mov_b32_e32 v156, v153
	v_mov_b32_e32 v136, v83
	v_pk_mul_f32 v[162:163], v[82:83], v[156:157]
	v_pk_mul_f32 v[82:83], v[136:137], v[156:157]
	v_mov_b32_e32 v135, v162
	v_mov_b32_e32 v151, v163
	v_mov_b32_e32 v153, v82
	v_mov_b32_e32 v155, v83
	v_pk_add_f32 v[134:135], v[134:135], v[150:151] neg_lo:[0,1] neg_hi:[0,1]
	v_pk_add_f32 v[82:83], v[152:153], v[154:155]
	s_waitcnt vmcnt(14)
	v_mov_b32_e32 v150, v188
	v_mov_b32_e32 v151, v189
	v_mov_b32_e32 v152, v190
	v_mov_b32_e32 v153, v191
	v_mov_b32_e32 v154, v192
	v_mov_b32_e32 v155, v193
	v_mov_b32_e32 v156, v194
	v_mov_b32_e32 v157, v195
	global_load_dwordx4 v[188:191], v236, s[34:35] offset:64
	global_load_dwordx4 v[192:195], v236, s[36:37] offset:64
	v_add_u32_e32 v236, 0x1000, v236
	v_pk_mul_f32 v[136:137], v[72:73], v[154:155]
	s_nop 0
	v_pk_fma_f32 v[136:137], v[138:139], v[150:151], v[136:137] neg_lo:[0,0,1] neg_hi:[0,0,1]
	v_pk_mul_f32 v[138:139], v[138:139], v[154:155]
	v_mul_f32_e32 v154, v140, v156
	v_pk_fma_f32 v[72:73], v[72:73], v[150:151], v[138:139]
	v_mul_f32_e32 v138, v140, v152
	v_mul_f32_e32 v150, v74, v156
	v_mul_f32_e32 v152, v74, v152
	v_mov_b32_e32 v74, v141
	v_mov_b32_e32 v156, v153
	v_mov_b32_e32 v140, v75
	v_pk_mul_f32 v[158:159], v[74:75], v[156:157]
	v_pk_mul_f32 v[74:75], v[140:141], v[156:157]
	v_or_b32_e32 v140, 0x800, v2
	v_ashrrev_i32_e32 v141, 31, v140
	v_mov_b32_e32 v139, v158
	v_mov_b32_e32 v151, v159
	v_lshlrev_b64 v[140:141], 2, v[140:141]
	v_pk_add_f32 v[138:139], v[138:139], v[150:151] neg_lo:[0,1] neg_hi:[0,1]
	v_lshl_add_u64 v[150:151], s[34:35], 0, v[140:141]
	v_lshl_add_u64 v[140:141], s[36:37], 0, v[140:141]
	v_mov_b32_e32 v153, v74
	v_mov_b32_e32 v155, v75
	v_lshl_add_u64 v[158:159], v[150:151], 0, v[0:1]
	v_lshl_add_u64 v[160:161], v[140:141], 0, v[0:1]
	v_pk_add_f32 v[74:75], v[152:153], v[154:155]
	s_waitcnt vmcnt(14)
; __device__ void even_in_tile(const P& p, int li_even, int tm, int tn, char* smem) {
;     ...
; #pragma unroll
;     for (int i = 0; i < MI; ++i) {
;       const int s = s0 + MROW(i);
; #pragma unroll
;       for (int jj = 0; jj < 2; ++jj) {
;         const int d = wn * 32 + jj * 16 + g * 4;
;         const f32x4 c = *(const f32x4*)(ctab + s * 64 + d);
;         const f32x4 sn = *(const f32x4*)(stab + s * 64 + d);
; #pragma unroll
;         for (int r = 0; r < 4; ++r) {
;           const float a = acc[i][jj][r], bb = acc[i][jj + 2][r];
;           acc[i][jj][r] = a * c[r] - bb * sn[r];
;           acc[i][jj + 2][r] = bb * c[r] + a * sn[r];
;         }
;       }
;     }
;   }
	v_mov_b32_e32 v150, v196
	v_mov_b32_e32 v151, v197
	v_mov_b32_e32 v152, v198
	v_mov_b32_e32 v153, v199
	v_mov_b32_e32 v154, v200
	v_mov_b32_e32 v155, v201
	v_mov_b32_e32 v156, v202
	v_mov_b32_e32 v157, v203
	global_load_dwordx4 v[196:199], v236, s[34:35]
	global_load_dwordx4 v[200:203], v236, s[36:37]
	v_pk_mul_f32 v[140:141], v[68:69], v[154:155]
	s_nop 0
	v_pk_fma_f32 v[140:141], v[142:143], v[150:151], v[140:141] neg_lo:[0,0,1] neg_hi:[0,0,1]
	v_pk_mul_f32 v[142:143], v[142:143], v[154:155]
	v_mul_f32_e32 v154, v144, v156
	v_pk_fma_f32 v[68:69], v[68:69], v[150:151], v[142:143]
	v_mul_f32_e32 v142, v144, v152
	v_mul_f32_e32 v150, v70, v156
	v_mul_f32_e32 v152, v70, v152
	v_mov_b32_e32 v70, v145
	v_mov_b32_e32 v156, v153
	v_mov_b32_e32 v144, v71
	v_pk_mul_f32 v[162:163], v[70:71], v[156:157]
	v_pk_mul_f32 v[70:71], v[144:145], v[156:157]
	v_mov_b32_e32 v143, v162
	v_mov_b32_e32 v151, v163
	v_mov_b32_e32 v153, v70
	v_mov_b32_e32 v155, v71
	v_pk_add_f32 v[142:143], v[142:143], v[150:151] neg_lo:[0,1] neg_hi:[0,1]
	v_pk_add_f32 v[70:71], v[152:153], v[154:155]
	s_waitcnt vmcnt(14)
	v_mov_b32_e32 v150, v204
	v_mov_b32_e32 v151, v205
	v_mov_b32_e32 v152, v206
	v_mov_b32_e32 v153, v207
	v_mov_b32_e32 v154, v220
	v_mov_b32_e32 v155, v221
	v_mov_b32_e32 v156, v222
	v_mov_b32_e32 v157, v223
	global_load_dwordx4 v[204:207], v236, s[34:35] offset:64
	global_load_dwordx4 v[220:223], v236, s[36:37] offset:64
	v_add_u32_e32 v236, 0x1000, v236
	v_pk_mul_f32 v[144:145], v[64:65], v[154:155]
	s_nop 0
	v_pk_fma_f32 v[144:145], v[146:147], v[150:151], v[144:145] neg_lo:[0,0,1] neg_hi:[0,0,1]
	v_pk_mul_f32 v[146:147], v[146:147], v[154:155]
	v_mul_f32_e32 v154, v148, v156
	v_pk_fma_f32 v[64:65], v[64:65], v[150:151], v[146:147]
	v_mul_f32_e32 v146, v148, v152
	v_mul_f32_e32 v150, v66, v156
	v_mul_f32_e32 v152, v66, v152
	v_mov_b32_e32 v66, v149
	v_mov_b32_e32 v156, v153
	v_mov_b32_e32 v148, v67
	v_pk_mul_f32 v[158:159], v[66:67], v[156:157]
	v_pk_mul_f32 v[66:67], v[148:149], v[156:157]
	v_or_b32_e32 v148, 0xc00, v2
	v_ashrrev_i32_e32 v149, 31, v148
	v_mov_b32_e32 v147, v158
	v_mov_b32_e32 v151, v159
	v_lshlrev_b64 v[148:149], 2, v[148:149]
	v_pk_add_f32 v[146:147], v[146:147], v[150:151] neg_lo:[0,1] neg_hi:[0,1]
	v_lshl_add_u64 v[150:151], s[34:35], 0, v[148:149]
	v_lshl_add_u64 v[148:149], s[36:37], 0, v[148:149]
	v_mov_b32_e32 v153, v66
	v_mov_b32_e32 v155, v67
	v_lshl_add_u64 v[158:159], v[150:151], 0, v[0:1]
	v_lshl_add_u64 v[160:161], v[148:149], 0, v[0:1]
	v_pk_add_f32 v[66:67], v[152:153], v[154:155]
	s_waitcnt vmcnt(14)
	v_mov_b32_e32 v150, v224
	v_mov_b32_e32 v151, v225
	v_mov_b32_e32 v152, v226
	v_mov_b32_e32 v153, v227
	v_mov_b32_e32 v154, v228
	v_mov_b32_e32 v155, v229
	v_mov_b32_e32 v156, v230
	v_mov_b32_e32 v157, v231
	global_load_dwordx4 v[224:227], v236, s[34:35]
	global_load_dwordx4 v[228:231], v236, s[36:37]
	v_pk_mul_f32 v[148:149], v[60:61], v[154:155]
	s_nop 0
	v_pk_fma_f32 v[148:149], v[128:129], v[150:151], v[148:149] neg_lo:[0,0,1] neg_hi:[0,0,1]
	v_pk_mul_f32 v[128:129], v[128:129], v[154:155]
	v_mul_f32_e32 v154, v130, v156
	v_pk_fma_f32 v[60:61], v[60:61], v[150:151], v[128:129]
	v_mul_f32_e32 v128, v130, v152
	v_mul_f32_e32 v150, v62, v156
	v_mul_f32_e32 v152, v62, v152
	v_mov_b32_e32 v62, v131
	v_mov_b32_e32 v156, v153
	v_mov_b32_e32 v130, v63
	v_pk_mul_f32 v[162:163], v[62:63], v[156:157]
	v_pk_mul_f32 v[62:63], v[130:131], v[156:157]
	v_mov_b32_e32 v129, v162
	v_mov_b32_e32 v153, v62
	v_mov_b32_e32 v155, v63
	v_pk_add_f32 v[62:63], v[152:153], v[154:155]
	s_nop 0
	v_mov_b32_e32 v151, v163
	v_pk_add_f32 v[150:151], v[128:129], v[150:151] neg_lo:[0,1] neg_hi:[0,1]
	s_waitcnt vmcnt(14)
	v_mov_b32_e32 v152, v232
	v_mov_b32_e32 v153, v233
	v_mov_b32_e32 v154, v234
	v_mov_b32_e32 v155, v235
	v_mov_b32_e32 v156, v4
	v_mov_b32_e32 v157, v5
	v_mov_b32_e32 v158, v6
	v_mov_b32_e32 v159, v7
	global_load_dwordx4 v[232:235], v236, s[34:35] offset:64
	global_load_dwordx4 v[4:7], v236, s[36:37] offset:64
	v_pk_mul_f32 v[128:129], v[56:57], v[156:157]
	s_nop 0
	v_pk_fma_f32 v[128:129], v[120:121], v[152:153], v[128:129] neg_lo:[0,0,1] neg_hi:[0,0,1]
	v_pk_mul_f32 v[120:121], v[120:121], v[156:157]
	v_mul_f32_e32 v130, v58, v158
	v_pk_fma_f32 v[56:57], v[56:57], v[152:153], v[120:121]
	v_mul_f32_e32 v120, v122, v154
	v_mul_f32_e32 v152, v58, v154
	v_mul_f32_e32 v154, v122, v158
	v_mov_b32_e32 v58, v123
	v_mov_b32_e32 v158, v155
	v_pk_mul_f32 v[156:157], v[58:59], v[158:159]
	v_mov_b32_e32 v122, v59
	v_mov_b32_e32 v121, v156
	v_mov_b32_e32 v131, v157
	v_pk_add_f32 v[130:131], v[120:121], v[130:131] neg_lo:[0,1] neg_hi:[0,1]
	v_or_b32_e32 v120, 0x1000, v2
	v_ashrrev_i32_e32 v121, 31, v120
	v_lshlrev_b64 v[120:121], 2, v[120:121]
	v_pk_mul_f32 v[58:59], v[122:123], v[158:159]
	v_lshl_add_u64 v[122:123], s[34:35], 0, v[120:121]
	v_lshl_add_u64 v[120:121], s[36:37], 0, v[120:121]
	v_mov_b32_e32 v153, v58
	v_mov_b32_e32 v155, v59
	v_lshl_add_u64 v[160:161], v[122:123], 0, v[0:1]
	v_lshl_add_u64 v[162:163], v[120:121], 0, v[0:1]
	v_pk_add_f32 v[58:59], v[152:153], v[154:155]
	s_waitcnt vmcnt(14)
	v_mov_b32_e32 v152, v164
	v_mov_b32_e32 v153, v165
	v_mov_b32_e32 v154, v166
	v_mov_b32_e32 v155, v167
	v_mov_b32_e32 v156, v168
	v_mov_b32_e32 v157, v169
	v_mov_b32_e32 v158, v170
	v_mov_b32_e32 v159, v171
	v_pk_mul_f32 v[120:121], v[52:53], v[156:157]
	s_nop 0
	v_pk_fma_f32 v[120:121], v[112:113], v[152:153], v[120:121] neg_lo:[0,0,1] neg_hi:[0,0,1]
	v_pk_mul_f32 v[112:113], v[112:113], v[156:157]
	v_mul_f32_e32 v122, v54, v158
	v_pk_fma_f32 v[52:53], v[52:53], v[152:153], v[112:113]
	v_mul_f32_e32 v112, v114, v154
	v_mul_f32_e32 v152, v54, v154
	v_mul_f32_e32 v154, v114, v158
	v_mov_b32_e32 v54, v115
	v_mov_b32_e32 v158, v155
	v_mov_b32_e32 v114, v55
	v_pk_mul_f32 v[156:157], v[54:55], v[158:159]
	v_pk_mul_f32 v[54:55], v[114:115], v[158:159]
	v_mov_b32_e32 v113, v156
	v_mov_b32_e32 v153, v54
	v_mov_b32_e32 v155, v55
	v_mov_b32_e32 v123, v157
	v_pk_add_f32 v[54:55], v[152:153], v[154:155]
	v_pk_add_f32 v[122:123], v[112:113], v[122:123] neg_lo:[0,1] neg_hi:[0,1]
	s_waitcnt vmcnt(12)
; __device__ void even_in_tile(const P& p, int li_even, int tm, int tn, char* smem) {
;     ...
; #pragma unroll
;     for (int i = 0; i < MI; ++i) {
;       const int s = s0 + MROW(i);
; #pragma unroll
;       for (int jj = 0; jj < 2; ++jj) {
;         const int d = wn * 32 + jj * 16 + g * 4;
;         const f32x4 c = *(const f32x4*)(ctab + s * 64 + d);
;         const f32x4 sn = *(const f32x4*)(stab + s * 64 + d);
; #pragma unroll
;         for (int r = 0; r < 4; ++r) {
;           const float a = acc[i][jj][r], bb = acc[i][jj + 2][r];
;           acc[i][jj][r] = a * c[r] - bb * sn[r];
;           acc[i][jj + 2][r] = bb * c[r] + a * sn[r];
;         }
;       }
;     }
;   }
	v_mov_b32_e32 v152, v172
	v_mov_b32_e32 v153, v173
	v_mov_b32_e32 v154, v174
	v_mov_b32_e32 v155, v175
	v_mov_b32_e32 v156, v176
	v_mov_b32_e32 v157, v177
	v_mov_b32_e32 v158, v178
	v_mov_b32_e32 v159, v179
	v_pk_mul_f32 v[112:113], v[48:49], v[156:157]
	s_nop 0
	v_pk_fma_f32 v[112:113], v[108:109], v[152:153], v[112:113] neg_lo:[0,0,1] neg_hi:[0,0,1]
	v_pk_mul_f32 v[108:109], v[108:109], v[156:157]
	v_mul_f32_e32 v114, v50, v158
	v_pk_fma_f32 v[48:49], v[48:49], v[152:153], v[108:109]
	v_mul_f32_e32 v108, v110, v154
	v_mul_f32_e32 v152, v50, v154
	v_mul_f32_e32 v154, v110, v158
	v_mov_b32_e32 v50, v111
	v_mov_b32_e32 v158, v155
	v_pk_mul_f32 v[156:157], v[50:51], v[158:159]
	v_mov_b32_e32 v110, v51
	v_mov_b32_e32 v109, v156
	v_mov_b32_e32 v115, v157
	v_pk_add_f32 v[114:115], v[108:109], v[114:115] neg_lo:[0,1] neg_hi:[0,1]
	v_or_b32_e32 v108, 0x1400, v2
	v_ashrrev_i32_e32 v109, 31, v108
	v_lshlrev_b64 v[108:109], 2, v[108:109]
	v_pk_mul_f32 v[50:51], v[110:111], v[158:159]
	v_lshl_add_u64 v[110:111], s[34:35], 0, v[108:109]
	v_lshl_add_u64 v[108:109], s[36:37], 0, v[108:109]
	v_mov_b32_e32 v153, v50
	v_mov_b32_e32 v155, v51
	v_lshl_add_u64 v[160:161], v[110:111], 0, v[0:1]
	v_lshl_add_u64 v[162:163], v[108:109], 0, v[0:1]
	v_pk_add_f32 v[50:51], v[152:153], v[154:155]
	s_waitcnt vmcnt(10)
	v_mov_b32_e32 v152, v180
	v_mov_b32_e32 v153, v181
	v_mov_b32_e32 v154, v182
	v_mov_b32_e32 v155, v183
	v_mov_b32_e32 v156, v184
	v_mov_b32_e32 v157, v185
	v_mov_b32_e32 v158, v186
	v_mov_b32_e32 v159, v187
	v_pk_mul_f32 v[108:109], v[44:45], v[156:157]
	s_nop 0
	v_pk_fma_f32 v[108:109], v[104:105], v[152:153], v[108:109] neg_lo:[0,0,1] neg_hi:[0,0,1]
	v_pk_mul_f32 v[104:105], v[104:105], v[156:157]
	v_mul_f32_e32 v110, v46, v158
	v_pk_fma_f32 v[44:45], v[44:45], v[152:153], v[104:105]
	v_mul_f32_e32 v104, v106, v154
	v_mul_f32_e32 v152, v46, v154
	v_mul_f32_e32 v154, v106, v158
	v_mov_b32_e32 v46, v107
	v_mov_b32_e32 v158, v155
	v_mov_b32_e32 v106, v47
	v_pk_mul_f32 v[156:157], v[46:47], v[158:159]
	v_pk_mul_f32 v[46:47], v[106:107], v[158:159]
	v_mov_b32_e32 v105, v156
	v_mov_b32_e32 v153, v46
	v_mov_b32_e32 v155, v47
	v_mov_b32_e32 v111, v157
	v_pk_add_f32 v[46:47], v[152:153], v[154:155]
	v_pk_add_f32 v[110:111], v[104:105], v[110:111] neg_lo:[0,1] neg_hi:[0,1]
	s_waitcnt vmcnt(8)
	v_mov_b32_e32 v152, v188
	v_mov_b32_e32 v153, v189
	v_mov_b32_e32 v154, v190
	v_mov_b32_e32 v155, v191
	v_mov_b32_e32 v156, v192
	v_mov_b32_e32 v157, v193
	v_mov_b32_e32 v158, v194
	v_mov_b32_e32 v159, v195
	v_pk_mul_f32 v[104:105], v[40:41], v[156:157]
	s_nop 0
	v_pk_fma_f32 v[104:105], v[100:101], v[152:153], v[104:105] neg_lo:[0,0,1] neg_hi:[0,0,1]
	v_pk_mul_f32 v[100:101], v[100:101], v[156:157]
	v_mul_f32_e32 v106, v42, v158
	v_pk_fma_f32 v[40:41], v[40:41], v[152:153], v[100:101]
	v_mul_f32_e32 v100, v102, v154
	v_mul_f32_e32 v152, v42, v154
	v_mul_f32_e32 v154, v102, v158
	v_mov_b32_e32 v42, v103
	v_mov_b32_e32 v158, v155
	v_pk_mul_f32 v[156:157], v[42:43], v[158:159]
	v_mov_b32_e32 v102, v43
	v_mov_b32_e32 v101, v156
	v_mov_b32_e32 v107, v157
	v_pk_add_f32 v[106:107], v[100:101], v[106:107] neg_lo:[0,1] neg_hi:[0,1]
	v_or_b32_e32 v100, 0x1800, v2
	v_ashrrev_i32_e32 v101, 31, v100
	v_lshlrev_b64 v[100:101], 2, v[100:101]
	v_pk_mul_f32 v[42:43], v[102:103], v[158:159]
	v_lshl_add_u64 v[102:103], s[34:35], 0, v[100:101]
	v_lshl_add_u64 v[100:101], s[36:37], 0, v[100:101]
	v_mov_b32_e32 v153, v42
	v_mov_b32_e32 v155, v43
	v_lshl_add_u64 v[160:161], v[102:103], 0, v[0:1]
	v_lshl_add_u64 v[162:163], v[100:101], 0, v[0:1]
	v_pk_add_f32 v[42:43], v[152:153], v[154:155]
	v_or_b32_e32 v2, 0x1c00, v2
	v_ashrrev_i32_e32 v3, 31, v2
	v_lshlrev_b64 v[2:3], 2, v[2:3]
	s_waitcnt vmcnt(6)
	v_mov_b32_e32 v152, v196
	v_mov_b32_e32 v153, v197
	v_mov_b32_e32 v154, v198
	v_mov_b32_e32 v155, v199
	v_mov_b32_e32 v156, v200
	v_mov_b32_e32 v157, v201
	v_mov_b32_e32 v158, v202
	v_mov_b32_e32 v159, v203
	v_pk_mul_f32 v[100:101], v[36:37], v[156:157]
	s_nop 0
	v_pk_fma_f32 v[100:101], v[96:97], v[152:153], v[100:101] neg_lo:[0,0,1] neg_hi:[0,0,1]
	v_pk_mul_f32 v[96:97], v[96:97], v[156:157]
	v_mul_f32_e32 v102, v38, v158
	v_pk_fma_f32 v[36:37], v[36:37], v[152:153], v[96:97]
	v_mul_f32_e32 v96, v98, v154
	v_mul_f32_e32 v152, v38, v154
	v_mul_f32_e32 v154, v98, v158
	v_mov_b32_e32 v38, v99
	v_mov_b32_e32 v158, v155
	v_mov_b32_e32 v98, v39
	v_pk_mul_f32 v[156:157], v[38:39], v[158:159]
	v_pk_mul_f32 v[38:39], v[98:99], v[158:159]
	v_mov_b32_e32 v97, v156
	v_mov_b32_e32 v153, v38
	v_mov_b32_e32 v155, v39
	v_mov_b32_e32 v103, v157
	v_pk_add_f32 v[38:39], v[152:153], v[154:155]
	v_pk_add_f32 v[102:103], v[96:97], v[102:103] neg_lo:[0,1] neg_hi:[0,1]
	s_waitcnt vmcnt(4)
; __device__ void even_in_tile(const P& p, int li_even, int tm, int tn, char* smem) {
;     ...
; #pragma unroll
;     for (int i = 0; i < MI; ++i) {
;       const int s = s0 + MROW(i);
; #pragma unroll
;       for (int jj = 0; jj < 2; ++jj) {
;         const int d = wn * 32 + jj * 16 + g * 4;
;         const f32x4 c = *(const f32x4*)(ctab + s * 64 + d);
;         const f32x4 sn = *(const f32x4*)(stab + s * 64 + d);
; #pragma unroll
;         for (int r = 0; r < 4; ++r) {
;           const float a = acc[i][jj][r], bb = acc[i][jj + 2][r];
;           acc[i][jj][r] = a * c[r] - bb * sn[r];
;           acc[i][jj + 2][r] = bb * c[r] + a * sn[r];
;         }
;       }
;     }
;   }
;   if (seg == 1) {
	v_mov_b32_e32 v152, v204
	v_mov_b32_e32 v153, v205
	v_mov_b32_e32 v154, v206
	v_mov_b32_e32 v155, v207
	v_mov_b32_e32 v156, v220
	v_mov_b32_e32 v157, v221
	v_mov_b32_e32 v158, v222
	v_mov_b32_e32 v159, v223
	v_pk_mul_f32 v[96:97], v[32:33], v[156:157]
	s_nop 0
	v_pk_fma_f32 v[96:97], v[92:93], v[152:153], v[96:97] neg_lo:[0,0,1] neg_hi:[0,0,1]
	v_pk_mul_f32 v[92:93], v[92:93], v[156:157]
	v_mul_f32_e32 v98, v34, v158
	v_pk_fma_f32 v[32:33], v[32:33], v[152:153], v[92:93]
	v_mul_f32_e32 v92, v94, v154
	v_mul_f32_e32 v152, v34, v154
	v_mul_f32_e32 v154, v94, v158
	v_mov_b32_e32 v34, v95
	v_mov_b32_e32 v158, v155
	v_pk_mul_f32 v[156:157], v[34:35], v[158:159]
	v_mov_b32_e32 v94, v35
	v_mov_b32_e32 v93, v156
	v_mov_b32_e32 v99, v157
	v_pk_add_f32 v[98:99], v[92:93], v[98:99] neg_lo:[0,1] neg_hi:[0,1]
	v_pk_mul_f32 v[34:35], v[94:95], v[158:159]
	v_lshl_add_u64 v[92:93], s[34:35], 0, v[2:3]
	v_lshl_add_u64 v[2:3], s[36:37], 0, v[2:3]
	v_mov_b32_e32 v153, v34
	v_mov_b32_e32 v155, v35
	v_lshl_add_u64 v[160:161], v[92:93], 0, v[0:1]
	v_lshl_add_u64 v[2:3], v[2:3], 0, v[0:1]
	v_pk_add_f32 v[34:35], v[152:153], v[154:155]
	s_waitcnt vmcnt(2)
	v_mov_b32_e32 v152, v224
	v_mov_b32_e32 v153, v225
	v_mov_b32_e32 v154, v226
	v_mov_b32_e32 v155, v227
	v_mov_b32_e32 v156, v228
	v_mov_b32_e32 v157, v229
	v_mov_b32_e32 v158, v230
	v_mov_b32_e32 v159, v231
	v_pk_mul_f32 v[92:93], v[24:25], v[156:157]
	s_nop 0
	v_pk_fma_f32 v[92:93], v[76:77], v[152:153], v[92:93] neg_lo:[0,0,1] neg_hi:[0,0,1]
	v_pk_mul_f32 v[76:77], v[76:77], v[156:157]
	v_mul_f32_e32 v94, v26, v158
	v_pk_fma_f32 v[24:25], v[24:25], v[152:153], v[76:77]
	v_mul_f32_e32 v76, v78, v154
	v_mul_f32_e32 v152, v26, v154
	v_mul_f32_e32 v154, v78, v158
	v_mov_b32_e32 v26, v79
	v_mov_b32_e32 v158, v155
	v_mov_b32_e32 v78, v27
	v_pk_mul_f32 v[156:157], v[26:27], v[158:159]
	v_pk_mul_f32 v[26:27], v[78:79], v[158:159]
	v_mov_b32_e32 v77, v156
	v_mov_b32_e32 v95, v157
	v_mov_b32_e32 v153, v26
	v_mov_b32_e32 v155, v27
	v_pk_add_f32 v[94:95], v[76:77], v[94:95] neg_lo:[0,1] neg_hi:[0,1]
	v_pk_add_f32 v[26:27], v[152:153], v[154:155]
	s_waitcnt vmcnt(0)
	v_mov_b32_e32 v76, v232
	v_mov_b32_e32 v77, v233
	v_mov_b32_e32 v78, v234
	v_mov_b32_e32 v79, v235
	v_mov_b32_e32 v152, v4
	v_mov_b32_e32 v153, v5
	v_mov_b32_e32 v154, v6
	v_mov_b32_e32 v155, v7
	v_pk_mul_f32 v[2:3], v[20:21], v[152:153]
	s_nop 0
	v_pk_fma_f32 v[156:157], v[28:29], v[76:77], v[2:3] neg_lo:[0,0,1] neg_hi:[0,0,1]
	v_pk_mul_f32 v[2:3], v[28:29], v[152:153]
	v_mul_f32_e32 v28, v22, v154
	v_pk_fma_f32 v[20:21], v[20:21], v[76:77], v[2:3]
	v_mul_f32_e32 v2, v30, v78
	v_mul_f32_e32 v76, v22, v78
	v_mul_f32_e32 v78, v30, v154
	v_mov_b32_e32 v22, v31
	v_mov_b32_e32 v154, v79
	v_pk_mul_f32 v[152:153], v[22:23], v[154:155]
	v_mov_b32_e32 v30, v23
	v_mov_b32_e32 v3, v152
	v_mov_b32_e32 v29, v153
	v_pk_add_f32 v[158:159], v[2:3], v[28:29] neg_lo:[0,1] neg_hi:[0,1]
	v_pk_mul_f32 v[2:3], v[30:31], v[154:155]
	v_mov_b64_e32 v[28:29], v[156:157]
	v_mov_b32_e32 v77, v2
	v_mov_b32_e32 v79, v3
	v_pk_add_f32 v[22:23], v[76:77], v[78:79]
	v_mov_b64_e32 v[76:77], v[92:93]
	v_mov_b64_e32 v[78:79], v[94:95]
	v_mov_b64_e32 v[92:93], v[96:97]
	v_mov_b64_e32 v[94:95], v[98:99]
	v_mov_b64_e32 v[96:97], v[100:101]
	v_mov_b64_e32 v[98:99], v[102:103]
	v_mov_b64_e32 v[100:101], v[104:105]
	v_mov_b64_e32 v[102:103], v[106:107]
	v_mov_b64_e32 v[104:105], v[108:109]
	v_mov_b64_e32 v[106:107], v[110:111]
	v_mov_b64_e32 v[108:109], v[112:113]
	v_mov_b64_e32 v[110:111], v[114:115]
	v_mov_b64_e32 v[112:113], v[120:121]
	v_mov_b64_e32 v[114:115], v[122:123]
	v_mov_b64_e32 v[120:121], v[128:129]
	v_mov_b64_e32 v[122:123], v[130:131]
	v_mov_b64_e32 v[128:129], v[148:149]
	v_mov_b64_e32 v[130:131], v[150:151]
	v_mov_b64_e32 v[148:149], v[146:147]
	v_mov_b64_e32 v[146:147], v[144:145]
	v_mov_b64_e32 v[144:145], v[142:143]
	v_mov_b64_e32 v[142:143], v[140:141]
	v_mov_b64_e32 v[140:141], v[138:139]
	v_mov_b64_e32 v[152:153], v[126:127]
	v_mov_b64_e32 v[138:139], v[136:137]
	v_mov_b64_e32 v[136:137], v[134:135]
	v_mov_b64_e32 v[150:151], v[124:125]
	v_mov_b64_e32 v[126:127], v[118:119]
	v_mov_b64_e32 v[30:31], v[158:159]
	v_mov_b64_e32 v[134:135], v[132:133]
	v_mov_b64_e32 v[124:125], v[116:117]
	s_cmp_eq_u32 s42, 1
	s_cselect_b64 s[34:35], -1, 0
	s_cmp_lg_u32 s42, 1
	s_cbranch_scc0 .LBB0_316

; __device__ __forceinline__ int otid() { int t = threadIdx.x; asm volatile("" : "+v"(t)); return t; }
; template <int MI, bool SWAP, bool F8 = false>
; __device__ __forceinline__ void gemm_core(const bf16_t* __restrict__ A, int lda, const bf16_t* __restrict__ B, int ldb,
;                                           int K, char* smem, f32x4 (&acc)[MI][4]) {
;   const int tid = otid(), lane = tid & 63, w = tid >> 6, wm = w >> 1, wn = w & 1;
;   const int lr = tid >> 3, lc = tid & 7;
;   const int li = lane & 15, g = lane >> 4;
;   u32x4 ra[MI], rb[4];
;   const bf16_t* ap = A + (size_t)lr * lda + lc * 8;
;   const bf16_t* bp = B + (size_t)lr * ldb + lc * 8;
; #pragma unroll
;   for (int i = 0; i < MI; ++i)
; #pragma unroll
;     for (int j = 0; j < 4; ++j) acc[i][j] = (f32x4){0.f, 0.f, 0.f, 0.f};
;   const int nk = K >> 6;
; #pragma unroll
;   for (int i = 0; i < MI; ++i) ra[i] = *(const u32x4*)(ap + (size_t)(32 * i) * lda);
; #pragma unroll
;   for (int i = 0; i < 4; ++i) rb[i] = *(const u32x4*)(bp + (size_t)(32 * i) * ldb);
;   const int woff = lr * 128 + ((lc ^ (lr & 7)) << 4);
;   const int xrow = (wm * 16 * MI + li) * 128;
;   const int wrow = 32768 + (wn * 32 + li) * 128;
; __device__ void even_in_tile(const P& p, int li_even, int tm, int tn, char* smem) {
;     ...
;   if (seg == 2 || seg == 5) {
;     gemm_core<MI, true>(A, 1024, B, 1024, 1024, smem, acc);
.LBB0_311:
	s_and_b64 vcc, exec, s[26:27]
	s_cbranch_vccz .LBB0_294
	s_waitcnt vmcnt(17)
	v_mov_b32_e32 v30, v208
	v_mov_b32_e32 v144, 0
	v_ashrrev_i32_e32 v2, 3, v30
	v_ashrrev_i32_e32 v3, 31, v2
	v_lshlrev_b64 v[20:21], 11, v[2:3]
	v_lshlrev_b32_e32 v0, 4, v30
	v_lshl_add_u64 v[24:25], s[20:21], 0, v[20:21]
	v_and_b32_e32 v0, 0x70, v0
	v_lshl_add_u64 v[24:25], v[24:25], 0, v[0:1]
	v_add_co_u32_e32 v26, vcc, 0x10000, v24
	v_lshl_add_u64 v[22:23], s[22:23], 0, v[20:21]
	s_nop 0
	v_addc_co_u32_e32 v27, vcc, 0, v25, vcc
	v_lshrrev_b32_e32 v254, 3, v208
	v_and_b32_e32 v254, 7, v254
	v_xor_b32_e32 v252, v254, v208
	v_and_b32_e32 v252, 7, v252
	v_lshlrev_b32_e32 v252, 4, v252
	v_lshl_or_b32 v252, v254, 11, v252
	v_add_u32_e32 v253, 0x10000, v252
	v_lshrrev_b32_e32 v254, 6, v208
	s_nop 0
	v_readfirstlane_b32 s62, v254
	s_lshl_b32 s62, s62, 10
	v_readfirstlane_b32 s56, v24
	v_readfirstlane_b32 s57, v25
	v_lshrrev_b32_e32 v222, 6, v208
	v_and_b32_e32 v223, 63, v208
	v_mul_u32_u24_e32 v222, 56, v222
	v_add_u32_e32 v222, v222, v223
	v_lshlrev_b32_e32 v222, 11, v222
	v_add_co_u32_e32 v26, vcc, 0x20000, v24
	v_lshl_add_u64 v[22:23], v[22:23], 0, v[0:1]
	s_nop 0
	v_addc_co_u32_e32 v27, vcc, 0, v25, vcc
	v_add_co_u32_e32 v28, vcc, 0x30000, v24
	s_add_i32 s20, s43, s44
	s_nop 0
	v_addc_co_u32_e32 v29, vcc, 0, v25, vcc
	v_add_co_u32_e32 v26, vcc, 0x40000, v24
	s_ashr_i32 s21, s20, 31
	s_nop 0
	v_addc_co_u32_e32 v27, vcc, 0, v25, vcc
	v_add_co_u32_e32 v28, vcc, 0x50000, v24
	s_lshl_b64 s[20:21], s[20:21], 19
	s_nop 0
	v_addc_co_u32_e32 v29, vcc, 0, v25, vcc
	v_add_co_u32_e32 v26, vcc, 0x60000, v24
	s_add_u32 s20, s8, s20
	s_nop 0
	v_addc_co_u32_e32 v27, vcc, 0, v25, vcc
	v_add_co_u32_e32 v24, vcc, 0x70000, v24
	v_and_b32_e32 v3, 15, v30
	s_nop 0
	v_addc_co_u32_e32 v25, vcc, 0, v25, vcc
	v_add_co_u32_e32 v24, vcc, s93, v22
	s_addc_u32 s21, s9, s21
	s_nop 0
	v_addc_co_u32_e32 v25, vcc, 0, v23, vcc
	s_nop 0
	v_readfirstlane_b32 s58, v22
	v_readfirstlane_b32 s59, v23
	v_add_co_u32_e32 v24, vcc, s46, v22
	v_lshrrev_b32_e32 v31, 4, v30
	s_nop 0
	v_addc_co_u32_e32 v25, vcc, 0, v23, vcc
	v_add_co_u32_e32 v22, vcc, s47, v22
	v_bfe_u32 v0, v30, 4, 2
	s_nop 0
	v_addc_co_u32_e32 v23, vcc, 0, v23, vcc
	v_lshlrev_b32_e32 v22, 7, v2
	v_xor_b32_e32 v2, v2, v30
	v_lshlrev_b32_e32 v2, 4, v2
	v_and_or_b32 v202, v2, s33, v22
	v_lshlrev_b32_e32 v2, 7, v30
	v_and_b32_e32 v203, 0xffffc780, v2
	v_lshrrev_b32_e32 v2, 1, v30
	v_and_or_b32 v2, v2, 32, v3
	v_and_b32_e32 v22, 7, v30
	s_add_u32 s8, s8, s10
	v_lshlrev_b32_e32 v204, 7, v2
	v_bitop3_b32 v2, v31, v22, 3 bitop3:0x6c
	v_bitop3_b32 v0, v0, v22, 4 bitop3:0x36
	s_addc_u32 s9, s9, s11
	v_lshlrev_b32_e32 v205, 4, v2
	v_lshlrev_b32_e32 v206, 4, v0
	v_lshl_add_u64 v[2:3], s[20:21], 0, v[20:21]
	v_lshlrev_b32_e32 v0, 4, v22
	v_lshl_add_u64 v[20:21], s[8:9], 0, v[20:21]
	v_lshl_add_u64 v[2:3], v[2:3], 0, v[0:1]
	v_lshl_add_u64 v[20:21], v[20:21], 0, v[0:1]
	v_lshl_add_u64 v[2:3], s[68:69], 0, v[2:3]
	v_lshl_add_u64 v[200:201], s[0:1], 0, v[20:21]
	s_mov_b64 s[8:9], 0
	v_mov_b32_e32 v145, v144
	v_mov_b32_e32 v146, v144
	v_mov_b32_e32 v147, v144
	v_mov_b32_e32 v20, v144
	v_mov_b32_e32 v21, v144
	v_mov_b32_e32 v22, v144
	v_mov_b32_e32 v23, v144
	s_waitcnt vmcnt(23)
	v_mov_b32_e32 v56, v144
	v_mov_b32_e32 v57, v144
	v_mov_b32_e32 v58, v144
	v_mov_b32_e32 v59, v144
	v_mov_b32_e32 v68, v144
	v_mov_b32_e32 v69, v144
	v_mov_b32_e32 v70, v144
	v_mov_b32_e32 v71, v144
	v_mov_b32_e32 v76, v144
	v_mov_b32_e32 v77, v144
	v_mov_b32_e32 v78, v144
	v_mov_b32_e32 v79, v144
	s_waitcnt vmcnt(21)
	v_mov_b32_e32 v84, v144
	v_mov_b32_e32 v85, v144
	v_mov_b32_e32 v86, v144
	v_mov_b32_e32 v87, v144
	v_mov_b32_e32 v24, v144
	v_mov_b32_e32 v25, v144
	v_mov_b32_e32 v26, v144
	v_mov_b32_e32 v27, v144
	v_mov_b32_e32 v28, v144
	v_mov_b32_e32 v29, v144
	v_mov_b32_e32 v30, v144
	v_mov_b32_e32 v31, v144
	v_mov_b32_e32 v32, v144
	v_mov_b32_e32 v33, v144
	v_mov_b32_e32 v34, v144
	v_mov_b32_e32 v35, v144
	v_mov_b32_e32 v36, v144
	v_mov_b32_e32 v37, v144
	v_mov_b32_e32 v38, v144
	v_mov_b32_e32 v39, v144
	v_mov_b32_e32 v40, v144
	v_mov_b32_e32 v41, v144
	v_mov_b32_e32 v42, v144
	v_mov_b32_e32 v43, v144
	v_mov_b32_e32 v44, v144
	v_mov_b32_e32 v45, v144
	v_mov_b32_e32 v46, v144
	v_mov_b32_e32 v47, v144
	v_mov_b32_e32 v48, v144
	v_mov_b32_e32 v49, v144
	v_mov_b32_e32 v50, v144
	v_mov_b32_e32 v51, v144
	v_mov_b32_e32 v52, v144
	v_mov_b32_e32 v53, v144
	v_mov_b32_e32 v54, v144
	v_mov_b32_e32 v55, v144
	v_mov_b32_e32 v60, v144
	v_mov_b32_e32 v61, v144
	v_mov_b32_e32 v62, v144
	v_mov_b32_e32 v63, v144
	v_mov_b32_e32 v64, v144
	v_mov_b32_e32 v65, v144
	v_mov_b32_e32 v66, v144
	v_mov_b32_e32 v67, v144
	v_mov_b32_e32 v72, v144
	v_mov_b32_e32 v73, v144
	v_mov_b32_e32 v74, v144
	v_mov_b32_e32 v75, v144
	v_mov_b32_e32 v80, v144
	v_mov_b32_e32 v81, v144
	v_mov_b32_e32 v82, v144
	v_mov_b32_e32 v83, v144
	s_waitcnt vmcnt(20)
	v_mov_b32_e32 v88, v144
	v_mov_b32_e32 v89, v144
	v_mov_b32_e32 v90, v144
	v_mov_b32_e32 v91, v144
	v_mov_b32_e32 v92, v144
	v_mov_b32_e32 v93, v144
	v_mov_b32_e32 v94, v144
	v_mov_b32_e32 v95, v144
	v_mov_b32_e32 v96, v144
	v_mov_b32_e32 v97, v144
	v_mov_b32_e32 v98, v144
	v_mov_b32_e32 v99, v144
	v_mov_b32_e32 v100, v144
	v_mov_b32_e32 v101, v144
	v_mov_b32_e32 v102, v144
	v_mov_b32_e32 v103, v144
	v_mov_b32_e32 v104, v144
	v_mov_b32_e32 v105, v144
	v_mov_b32_e32 v106, v144
	v_mov_b32_e32 v107, v144
	v_mov_b32_e32 v108, v144
	v_mov_b32_e32 v109, v144
	v_mov_b32_e32 v110, v144
	v_mov_b32_e32 v111, v144
	v_mov_b32_e32 v112, v144
	v_mov_b32_e32 v113, v144
	v_mov_b32_e32 v114, v144
	v_mov_b32_e32 v115, v144
	v_mov_b32_e32 v116, v144
	v_mov_b32_e32 v117, v144
	v_mov_b32_e32 v118, v144
	v_mov_b32_e32 v119, v144
	v_mov_b32_e32 v120, v144
	v_mov_b32_e32 v121, v144
	v_mov_b32_e32 v122, v144
	v_mov_b32_e32 v123, v144
	v_mov_b32_e32 v124, v144
	v_mov_b32_e32 v125, v144
	v_mov_b32_e32 v126, v144
	v_mov_b32_e32 v127, v144
	v_mov_b32_e32 v128, v144
	v_mov_b32_e32 v129, v144
	v_mov_b32_e32 v130, v144
	v_mov_b32_e32 v131, v144
	v_mov_b32_e32 v132, v144
	v_mov_b32_e32 v133, v144
	v_mov_b32_e32 v134, v144
	v_mov_b32_e32 v135, v144
	v_mov_b32_e32 v136, v144
	v_mov_b32_e32 v137, v144
	v_mov_b32_e32 v138, v144
	v_mov_b32_e32 v139, v144
	v_mov_b32_e32 v140, v144
	v_mov_b32_e32 v141, v144
	v_mov_b32_e32 v142, v144
	v_mov_b32_e32 v143, v144
	s_mov_b32 s7, 0x284000
	s_mov_b32 s10, 0x294000
; template <int MI, bool SWAP, bool F8 = false>
; __device__ __forceinline__ void gemm_core(const bf16_t* __restrict__ A, int lda, const bf16_t* __restrict__ B, int ldb,
;                                           int K, char* smem, f32x4 (&acc)[MI][4]) {
;     ...
;   for (int kt = 0; kt < nk; ++kt) {
;     __syncthreads();
; #pragma unroll
;     for (int i = 0; i < MI; ++i) *(u32x4*)(smem + woff + i * 4096) = ra[i];
; #pragma unroll
;     for (int i = 0; i < 4; ++i) *(u32x4*)(smem + 32768 + woff + i * 4096) = rb[i];
;     __syncthreads();
;     if (kt + 1 < nk) {
; #pragma unroll
;       for (int i = 0; i < MI; ++i) ra[i] = *(const u32x4*)(ap + (size_t)(32 * i) * lda + (kt + 1) * 64);
; #pragma unroll
;       for (int i = 0; i < 4; ++i) rb[i] = *(const u32x4*)(bp + (size_t)(32 * i) * ldb + (kt + 1) * 64);
;     }
;     if (F8) {
;       const int c0 = (g ^ (li & 7)) << 4, c1 = ((4 + g) ^ (li & 7)) << 4;
;       i32x8 wf8[4];
; #pragma unroll
;       for (int j = 0; j < 4; ++j) {
;         const char* rp = smem + wrow + ((j & 1) * 16 + (j >> 1) * 64) * 128;
;         const u32x4 lo = *(const u32x4*)(rp + c0), hi = *(const u32x4*)(rp + c1);
;         wf8[j] = (i32x8){(int)lo.x, (int)lo.y, (int)lo.z, (int)lo.w, (int)hi.x, (int)hi.y, (int)hi.z, (int)hi.w};
;       }
; #pragma unroll
;       for (int i = 0; i < MI; ++i) {
;         const char* rp = smem + xrow + i * 2048;
;         const u32x4 lo = *(const u32x4*)(rp + c0), hi = *(const u32x4*)(rp + c1);
;         const i32x8 xf8 = {(int)lo.x, (int)lo.y, (int)lo.z, (int)lo.w, (int)hi.x, (int)hi.y, (int)hi.z, (int)hi.w};
; #pragma unroll
;         for (int j = 0; j < 4; ++j)
;           acc[i][j] = __builtin_amdgcn_mfma_scale_f32_16x16x128_f8f6f4(wf8[j], xf8, acc[i][j], 0, 0, 0, 0x77777777, 0, 0x7f7f7f7f);
;       }
;     } else {
; #pragma unroll
;     for (int kk = 0; kk < 2; ++kk) {
;       const int ch = ((kk * 4 + g) ^ (li & 7)) << 4;
;       bf16x8 xf[MI], wf[4];
; #pragma unroll
;       for (int j = 0; j < 4; ++j) wf[j] = *(const bf16x8*)(smem + wrow + ((j & 1) * 16 + (j >> 1) * 64) * 128 + ch);
; #pragma unroll
;       for (int i = 0; i < MI; ++i) xf[i] = *(const bf16x8*)(smem + xrow + i * 2048 + ch);
; #pragma unroll
;       for (int i = 0; i < MI; ++i)
; #pragma unroll
;         for (int j = 0; j < 4; ++j) {
.LBB0_313:
	v_add_u32_e32 v215, v204, v205
	v_add_u32_e32 v213, v203, v205
	s_waitcnt vmcnt(63) expcnt(7) lgkmcnt(15)
	s_barrier
	s_mov_b32 m0, s62
	s_nop 0
	global_load_lds_dwordx4 v252, s[56:57]
	s_add_u32 m0, s62, 0x1000
	s_nop 0
	global_load_lds_dwordx4 v253, s[56:57]
	s_add_u32 s56, s56, 0x20000
	s_addc_u32 s57, s57, 0
	s_add_u32 m0, s62, 0x2000
	s_nop 0
	global_load_lds_dwordx4 v252, s[56:57]
	s_add_u32 m0, s62, 0x3000
	s_nop 0
	global_load_lds_dwordx4 v253, s[56:57]
	s_add_u32 s56, s56, 0x20000
	s_addc_u32 s57, s57, 0
	s_add_u32 m0, s62, 0x4000
	s_nop 0
	global_load_lds_dwordx4 v252, s[56:57]
	s_add_u32 m0, s62, 0x5000
	s_nop 0
	global_load_lds_dwordx4 v253, s[56:57]
	s_add_u32 s56, s56, 0x20000
	s_addc_u32 s57, s57, 0
	s_add_u32 m0, s62, 0x6000
	s_nop 0
	global_load_lds_dwordx4 v252, s[56:57]
	s_add_u32 m0, s62, 0x7000
	s_nop 0
	global_load_lds_dwordx4 v253, s[56:57]
	s_sub_u32 s56, s56, 0x60000
	s_subb_u32 s57, s57, 0
	s_add_u32 m0, s62, 0x8000
	s_nop 0
	global_load_lds_dwordx4 v252, s[58:59]
	s_add_u32 m0, s62, 0x9000
	s_nop 0
	global_load_lds_dwordx4 v253, s[58:59]
	s_add_u32 s58, s58, 0x20000
	s_addc_u32 s59, s59, 0
	s_add_u32 m0, s62, 0xa000
	s_nop 0
	global_load_lds_dwordx4 v252, s[58:59]
	s_add_u32 m0, s62, 0xb000
	s_nop 0
	global_load_lds_dwordx4 v253, s[58:59]
	s_sub_u32 s58, s58, 0x20000
	s_subb_u32 s59, s59, 0
	v_add_u32_e32 v252, 0x80, v252
	v_add_u32_e32 v253, 0x80, v253
	global_load_dword v223, v222, s[56:57] offset:256
	v_add_u32_e32 v222, 0x80, v222
	s_waitcnt vmcnt(1)
	s_barrier
	ds_read_b128 v[148:151], v213
	ds_read_b128 v[152:155], v215 offset:32768
	ds_read_b128 v[156:159], v215 offset:34816
	ds_read_b128 v[160:163], v213 offset:2048
	ds_read_b128 v[164:167], v215 offset:40960
	ds_read_b128 v[168:171], v215 offset:43008
	s_waitcnt lgkmcnt(4)
	v_mfma_f32_16x16x32_bf16 v[140:143], v[148:151], v[152:155], v[140:143]
	v_add_u32_e32 v0, v203, v206
	v_add_u32_e32 v207, v204, v206
	s_waitcnt lgkmcnt(3)
	v_mfma_f32_16x16x32_bf16 v[136:139], v[148:151], v[156:159], v[136:139]
	s_waitcnt lgkmcnt(1)
	v_mfma_f32_16x16x32_bf16 v[132:135], v[148:151], v[164:167], v[132:135]
	s_waitcnt lgkmcnt(0)
	v_mfma_f32_16x16x32_bf16 v[128:131], v[148:151], v[168:171], v[128:131]
	v_mfma_f32_16x16x32_bf16 v[124:127], v[160:163], v[152:155], v[124:127]
	v_mfma_f32_16x16x32_bf16 v[120:123], v[160:163], v[156:159], v[120:123]
	v_mfma_f32_16x16x32_bf16 v[116:119], v[160:163], v[164:167], v[116:119]
	v_mfma_f32_16x16x32_bf16 v[112:115], v[160:163], v[168:171], v[112:115]
	ds_read_b128 v[148:151], v213 offset:4096
	ds_read_b128 v[160:163], v213 offset:6144
	s_waitcnt lgkmcnt(1)
	v_mfma_f32_16x16x32_bf16 v[108:111], v[148:151], v[152:155], v[108:111]
	v_mfma_f32_16x16x32_bf16 v[104:107], v[148:151], v[156:159], v[104:107]
	v_mfma_f32_16x16x32_bf16 v[100:103], v[148:151], v[164:167], v[100:103]
	v_mfma_f32_16x16x32_bf16 v[96:99], v[148:151], v[168:171], v[96:99]
	s_waitcnt lgkmcnt(0)
	v_mfma_f32_16x16x32_bf16 v[92:95], v[160:163], v[152:155], v[92:95]
	v_mfma_f32_16x16x32_bf16 v[88:91], v[160:163], v[156:159], v[88:91]
	v_mfma_f32_16x16x32_bf16 v[80:83], v[160:163], v[164:167], v[80:83]
	v_mfma_f32_16x16x32_bf16 v[72:75], v[160:163], v[168:171], v[72:75]
	ds_read_b128 v[148:151], v213 offset:8192
	ds_read_b128 v[160:163], v213 offset:10240
	s_waitcnt lgkmcnt(1)
	v_mfma_f32_16x16x32_bf16 v[64:67], v[148:151], v[152:155], v[64:67]
	v_mfma_f32_16x16x32_bf16 v[60:63], v[148:151], v[156:159], v[60:63]
	v_mfma_f32_16x16x32_bf16 v[52:55], v[148:151], v[164:167], v[52:55]
	v_mfma_f32_16x16x32_bf16 v[48:51], v[148:151], v[168:171], v[48:51]
	s_waitcnt lgkmcnt(0)
	v_mfma_f32_16x16x32_bf16 v[44:47], v[160:163], v[152:155], v[44:47]
	v_mfma_f32_16x16x32_bf16 v[40:43], v[160:163], v[156:159], v[40:43]
	v_mfma_f32_16x16x32_bf16 v[36:39], v[160:163], v[164:167], v[36:39]
	v_mfma_f32_16x16x32_bf16 v[32:35], v[160:163], v[168:171], v[32:35]
	ds_read_b128 v[148:151], v213 offset:12288
	ds_read_b128 v[160:163], v213 offset:14336
	s_waitcnt lgkmcnt(1)
	v_mfma_f32_16x16x32_bf16 v[24:27], v[148:151], v[156:159], v[24:27]
	s_waitcnt lgkmcnt(0)
	v_mfma_f32_16x16x32_bf16 v[56:59], v[160:163], v[156:159], v[56:59]
	v_mfma_f32_16x16x32_bf16 v[68:71], v[160:163], v[152:155], v[68:71]
	v_mfma_f32_16x16x32_bf16 v[20:23], v[160:163], v[164:167], v[20:23]
	v_mfma_f32_16x16x32_bf16 v[144:147], v[160:163], v[168:171], v[144:147]
	v_mfma_f32_16x16x32_bf16 v[28:31], v[148:151], v[152:155], v[28:31]
	v_mfma_f32_16x16x32_bf16 v[84:87], v[148:151], v[164:167], v[84:87]
	v_mfma_f32_16x16x32_bf16 v[76:79], v[148:151], v[168:171], v[76:79]
	ds_read_b128 v[148:151], v0
	ds_read_b128 v[168:171], v207 offset:32768
	ds_read_b128 v[180:183], v207 offset:34816
	ds_read_b128 v[152:155], v0 offset:2048
	ds_read_b128 v[192:195], v207 offset:40960
	ds_read_b128 v[196:199], v207 offset:43008
	s_waitcnt lgkmcnt(4)
	v_mfma_f32_16x16x32_bf16 v[140:143], v[148:151], v[168:171], v[140:143]
	s_waitcnt lgkmcnt(3)
	v_mfma_f32_16x16x32_bf16 v[136:139], v[148:151], v[180:183], v[136:139]
	s_waitcnt lgkmcnt(1)
	v_mfma_f32_16x16x32_bf16 v[132:135], v[148:151], v[192:195], v[132:135]
	s_waitcnt lgkmcnt(0)
	v_mfma_f32_16x16x32_bf16 v[128:131], v[148:151], v[196:199], v[128:131]
	v_mfma_f32_16x16x32_bf16 v[124:127], v[152:155], v[168:171], v[124:127]
	v_mfma_f32_16x16x32_bf16 v[120:123], v[152:155], v[180:183], v[120:123]
	v_mfma_f32_16x16x32_bf16 v[116:119], v[152:155], v[192:195], v[116:119]
	v_mfma_f32_16x16x32_bf16 v[112:115], v[152:155], v[196:199], v[112:115]
	ds_read_b128 v[148:151], v0 offset:4096
	ds_read_b128 v[152:155], v0 offset:6144
	ds_read_b128 v[156:159], v0 offset:12288
	ds_read_b128 v[216:219], v0 offset:14336
	s_waitcnt lgkmcnt(3)
; template <int MI, bool SWAP, bool F8 = false>
; __device__ __forceinline__ void gemm_core(const bf16_t* __restrict__ A, int lda, const bf16_t* __restrict__ B, int ldb,
;                                           int K, char* smem, f32x4 (&acc)[MI][4]) {
;     ...
;   for (int kt = 0; kt < nk; ++kt) {
;     __syncthreads();
; #pragma unroll
;     for (int i = 0; i < MI; ++i) *(u32x4*)(smem + woff + i * 4096) = ra[i];
; #pragma unroll
;     for (int i = 0; i < 4; ++i) *(u32x4*)(smem + 32768 + woff + i * 4096) = rb[i];
;     __syncthreads();
;     if (kt + 1 < nk) {
; #pragma unroll
;       for (int i = 0; i < MI; ++i) ra[i] = *(const u32x4*)(ap + (size_t)(32 * i) * lda + (kt + 1) * 64);
; #pragma unroll
;       for (int i = 0; i < 4; ++i) rb[i] = *(const u32x4*)(bp + (size_t)(32 * i) * ldb + (kt + 1) * 64);
;     }
;     if (F8) {
;       const int c0 = (g ^ (li & 7)) << 4, c1 = ((4 + g) ^ (li & 7)) << 4;
;       i32x8 wf8[4];
; #pragma unroll
;       for (int j = 0; j < 4; ++j) {
;         const char* rp = smem + wrow + ((j & 1) * 16 + (j >> 1) * 64) * 128;
;         const u32x4 lo = *(const u32x4*)(rp + c0), hi = *(const u32x4*)(rp + c1);
;         wf8[j] = (i32x8){(int)lo.x, (int)lo.y, (int)lo.z, (int)lo.w, (int)hi.x, (int)hi.y, (int)hi.z, (int)hi.w};
;       }
; #pragma unroll
;       for (int i = 0; i < MI; ++i) {
;         const char* rp = smem + xrow + i * 2048;
;         const u32x4 lo = *(const u32x4*)(rp + c0), hi = *(const u32x4*)(rp + c1);
;         const i32x8 xf8 = {(int)lo.x, (int)lo.y, (int)lo.z, (int)lo.w, (int)hi.x, (int)hi.y, (int)hi.z, (int)hi.w};
; #pragma unroll
;         for (int j = 0; j < 4; ++j)
;           acc[i][j] = __builtin_amdgcn_mfma_scale_f32_16x16x128_f8f6f4(wf8[j], xf8, acc[i][j], 0, 0, 0, 0x77777777, 0, 0x7f7f7f7f);
;       }
;     } else {
; #pragma unroll
;     for (int kk = 0; kk < 2; ++kk) {
;       const int ch = ((kk * 4 + g) ^ (li & 7)) << 4;
;       bf16x8 xf[MI], wf[4];
; #pragma unroll
;       for (int j = 0; j < 4; ++j) wf[j] = *(const bf16x8*)(smem + wrow + ((j & 1) * 16 + (j >> 1) * 64) * 128 + ch);
; #pragma unroll
;       for (int i = 0; i < MI; ++i) xf[i] = *(const bf16x8*)(smem + xrow + i * 2048 + ch);
; #pragma unroll
;       for (int i = 0; i < MI; ++i)
; #pragma unroll
;         for (int j = 0; j < 4; ++j) {
	v_mfma_f32_16x16x32_bf16 v[108:111], v[148:151], v[168:171], v[108:111]
	v_mfma_f32_16x16x32_bf16 v[104:107], v[148:151], v[180:183], v[104:107]
	v_mfma_f32_16x16x32_bf16 v[100:103], v[148:151], v[192:195], v[100:103]
	v_mfma_f32_16x16x32_bf16 v[96:99], v[148:151], v[196:199], v[96:99]
	ds_read_b128 v[148:151], v0 offset:8192
	s_waitcnt lgkmcnt(3)
	v_mfma_f32_16x16x32_bf16 v[92:95], v[152:155], v[168:171], v[92:95]
	v_mfma_f32_16x16x32_bf16 v[88:91], v[152:155], v[180:183], v[88:91]
	v_mfma_f32_16x16x32_bf16 v[80:83], v[152:155], v[192:195], v[80:83]
	v_mfma_f32_16x16x32_bf16 v[72:75], v[152:155], v[196:199], v[72:75]
	ds_read_b128 v[152:155], v0 offset:10240
	s_waitcnt lgkmcnt(1)
	v_mfma_f32_16x16x32_bf16 v[64:67], v[148:151], v[168:171], v[64:67]
	v_mfma_f32_16x16x32_bf16 v[60:63], v[148:151], v[180:183], v[60:63]
	v_mfma_f32_16x16x32_bf16 v[52:55], v[148:151], v[192:195], v[52:55]
	v_mfma_f32_16x16x32_bf16 v[48:51], v[148:151], v[196:199], v[48:51]
	s_waitcnt lgkmcnt(0)
	v_mfma_f32_16x16x32_bf16 v[44:47], v[152:155], v[168:171], v[44:47]
	v_mfma_f32_16x16x32_bf16 v[40:43], v[152:155], v[180:183], v[40:43]
	v_mfma_f32_16x16x32_bf16 v[36:39], v[152:155], v[192:195], v[36:39]
	v_mfma_f32_16x16x32_bf16 v[32:35], v[152:155], v[196:199], v[32:35]
	v_mfma_f32_16x16x32_bf16 v[28:31], v[156:159], v[168:171], v[28:31]
	v_mfma_f32_16x16x32_bf16 v[24:27], v[156:159], v[180:183], v[24:27]
	v_mfma_f32_16x16x32_bf16 v[84:87], v[156:159], v[192:195], v[84:87]
	v_mfma_f32_16x16x32_bf16 v[76:79], v[156:159], v[196:199], v[76:79]
	v_mfma_f32_16x16x32_bf16 v[68:71], v[216:219], v[168:171], v[68:71]
	v_mfma_f32_16x16x32_bf16 v[56:59], v[216:219], v[180:183], v[56:59]
	v_mfma_f32_16x16x32_bf16 v[20:23], v[216:219], v[192:195], v[20:23]
	v_mfma_f32_16x16x32_bf16 v[144:147], v[216:219], v[196:199], v[144:147]
	s_add_u32 s8, s8, 0x80
	s_addc_u32 s9, s9, 0
	s_cmpk_lg_i32 s8, 0x780
	s_cbranch_scc1 .LBB0_313
	s_barrier
	s_mov_b32 m0, s62
	s_nop 0
	global_load_lds_dwordx4 v252, s[56:57]
	s_add_u32 m0, s62, 0x1000
	s_nop 0
	global_load_lds_dwordx4 v253, s[56:57]
	s_add_u32 s56, s56, 0x20000
	s_addc_u32 s57, s57, 0
	s_add_u32 m0, s62, 0x2000
	s_nop 0
	global_load_lds_dwordx4 v252, s[56:57]
	s_add_u32 m0, s62, 0x3000
	s_nop 0
	global_load_lds_dwordx4 v253, s[56:57]
	s_add_u32 s56, s56, 0x20000
	s_addc_u32 s57, s57, 0
	s_add_u32 m0, s62, 0x4000
	s_nop 0
	global_load_lds_dwordx4 v252, s[56:57]
	s_add_u32 m0, s62, 0x5000
	s_nop 0
	global_load_lds_dwordx4 v253, s[56:57]
	s_add_u32 s56, s56, 0x20000
	s_addc_u32 s57, s57, 0
	s_add_u32 m0, s62, 0x6000
	s_nop 0
	global_load_lds_dwordx4 v252, s[56:57]
	s_add_u32 m0, s62, 0x7000
	s_nop 0
	global_load_lds_dwordx4 v253, s[56:57]
	s_sub_u32 s56, s56, 0x60000
	s_subb_u32 s57, s57, 0
	s_add_u32 m0, s62, 0x8000
	s_nop 0
	global_load_lds_dwordx4 v252, s[58:59]
	s_add_u32 m0, s62, 0x9000
	s_nop 0
	global_load_lds_dwordx4 v253, s[58:59]
	s_add_u32 s58, s58, 0x20000
	s_addc_u32 s59, s59, 0
	s_add_u32 m0, s62, 0xa000
	s_nop 0
	global_load_lds_dwordx4 v252, s[58:59]
	s_add_u32 m0, s62, 0xb000
	s_nop 0
	global_load_lds_dwordx4 v253, s[58:59]
	s_sub_u32 s58, s58, 0x20000
	s_subb_u32 s59, s59, 0
	s_waitcnt vmcnt(0)
	s_barrier
	v_bfe_u32 v12, v208, 4, 1
	v_mul_u32_u24_e32 v12, 24, v12
	v_mov_b32_e32 v13, 0
	ds_read_b128 v[148:151], v215 offset:32768
	ds_read_b128 v[152:155], v215 offset:34816
	ds_read_b128 v[156:159], v215 offset:40960
	ds_read_b128 v[160:163], v215 offset:43008
	ds_read_b128 v[164:167], v213
	ds_read_b128 v[168:171], v213 offset:2048
	ds_read_b128 v[172:175], v213 offset:4096
	ds_read_b128 v[176:179], v213 offset:6144
	ds_read_b128 v[180:183], v213 offset:8192
	ds_read_b128 v[184:187], v213 offset:10240
	ds_read_b128 v[188:191], v213 offset:12288
	ds_read_b128 v[192:195], v213 offset:14336
	s_cmp_eq_u32 s42, 2
	s_mov_b32 s7, 0x6000000
	s_cselect_b32 s7, 0x2000000, s7
	s_waitcnt lgkmcnt(7)
	v_mfma_f32_16x16x32_bf16 v[140:143], v[164:167], v[148:151], v[140:143]
	s_add_u32 s8, s40, s7
	s_addc_u32 s9, s39, 0
	s_ashr_i32 s7, s6, 31
	v_mfma_f32_16x16x32_bf16 v[136:139], v[164:167], v[152:155], v[136:139]
	s_lshl_b64 s[6:7], s[6:7], 20
	s_add_u32 s6, s8, s6
	s_addc_u32 s7, s9, s7
	v_mfma_f32_16x16x32_bf16 v[132:135], v[164:167], v[156:159], v[132:135]
	s_lshl_b32 s8, s41, 1
	s_add_u32 s6, s6, s8
	s_addc_u32 s7, s7, 0
	v_mfma_f32_16x16x32_bf16 v[128:131], v[164:167], v[160:163], v[128:131]
	s_waitcnt lgkmcnt(6)
	v_mfma_f32_16x16x32_bf16 v[124:127], v[168:171], v[148:151], v[124:127]
	v_mfma_f32_16x16x32_bf16 v[120:123], v[168:171], v[152:155], v[120:123]
	v_mfma_f32_16x16x32_bf16 v[116:119], v[168:171], v[156:159], v[116:119]
	v_mfma_f32_16x16x32_bf16 v[112:115], v[168:171], v[160:163], v[112:115]
	s_waitcnt lgkmcnt(5)
	v_mfma_f32_16x16x32_bf16 v[108:111], v[172:175], v[148:151], v[108:111]
	v_mfma_f32_16x16x32_bf16 v[104:107], v[172:175], v[152:155], v[104:107]
	v_mfma_f32_16x16x32_bf16 v[100:103], v[172:175], v[156:159], v[100:103]
	v_mfma_f32_16x16x32_bf16 v[96:99], v[172:175], v[160:163], v[96:99]
	s_waitcnt lgkmcnt(4)
	v_mfma_f32_16x16x32_bf16 v[92:95], v[176:179], v[148:151], v[92:95]
	v_mfma_f32_16x16x32_bf16 v[88:91], v[176:179], v[152:155], v[88:91]
	v_mfma_f32_16x16x32_bf16 v[80:83], v[176:179], v[156:159], v[80:83]
	v_mfma_f32_16x16x32_bf16 v[72:75], v[176:179], v[160:163], v[72:75]
	s_waitcnt lgkmcnt(3)
	v_mfma_f32_16x16x32_bf16 v[64:67], v[180:183], v[148:151], v[64:67]
	v_mfma_f32_16x16x32_bf16 v[60:63], v[180:183], v[152:155], v[60:63]
	v_mfma_f32_16x16x32_bf16 v[52:55], v[180:183], v[156:159], v[52:55]
	v_mfma_f32_16x16x32_bf16 v[48:51], v[180:183], v[160:163], v[48:51]
	s_waitcnt lgkmcnt(2)
; template <int MI, bool SWAP, bool F8 = false>
; __device__ __forceinline__ void gemm_core(const bf16_t* __restrict__ A, int lda, const bf16_t* __restrict__ B, int ldb,
;                                           int K, char* smem, f32x4 (&acc)[MI][4]) {
;     ...
;           if (SWAP) acc[i][j] = __builtin_amdgcn_mfma_f32_16x16x32_bf16(xf[i], wf[j], acc[i][j], 0, 0, 0);
; __device__ void even_in_tile(const P& p, int li_even, int tm, int tn, char* smem) {
;     ...
;   if (seg == 2 || seg == 5) {
;     gemm_core<MI, true>(A, 1024, B, 1024, 1024, smem, acc);
;     EPI_COORDS
;     bf16_t* dst = R + (seg == 2 ? R_MVT : R_RVT) + (size_t)bh * 128 * 4096;
; #pragma unroll
;     for (int i = 0; i < MI; ++i)
; #pragma unroll
;       for (int j = 0; j < 4; ++j) {
;         u32x2 v;
;         v.x = pk_bf16(acc[i][j][0], acc[i][j][1]);
;         v.y = pk_bf16(acc[i][j][2], acc[i][j][3]);
;         *(u32x2*)(dst + (size_t)NCOLS(j) * 4096 + s0 + MROWS(i)) = v;
;       }
	v_mfma_f32_16x16x32_bf16 v[44:47], v[184:187], v[148:151], v[44:47]
	v_mfma_f32_16x16x32_bf16 v[40:43], v[184:187], v[152:155], v[40:43]
	v_mfma_f32_16x16x32_bf16 v[36:39], v[184:187], v[156:159], v[36:39]
	v_mfma_f32_16x16x32_bf16 v[32:35], v[184:187], v[160:163], v[32:35]
	s_waitcnt lgkmcnt(1)
	v_mfma_f32_16x16x32_bf16 v[28:31], v[188:191], v[148:151], v[28:31]
	v_mfma_f32_16x16x32_bf16 v[24:27], v[188:191], v[152:155], v[24:27]
	v_mfma_f32_16x16x32_bf16 v[164:167], v[188:191], v[156:159], v[84:87]
	v_mfma_f32_16x16x32_bf16 v[168:171], v[188:191], v[160:163], v[76:79]
	s_waitcnt lgkmcnt(0)
	v_mfma_f32_16x16x32_bf16 v[148:151], v[192:195], v[148:151], v[68:71]
	v_mfma_f32_16x16x32_bf16 v[152:155], v[192:195], v[152:155], v[56:59]
	v_mfma_f32_16x16x32_bf16 v[20:23], v[192:195], v[156:159], v[20:23]
	v_mfma_f32_16x16x32_bf16 v[144:147], v[192:195], v[160:163], v[144:147]
	ds_read_b128 v[156:159], v207 offset:32768
	ds_read_b128 v[160:163], v207 offset:34816
	ds_read_b128 v[172:175], v207 offset:40960
	ds_read_b128 v[176:179], v207 offset:43008
	ds_read_b128 v[56:59], v0
	ds_read_b128 v[68:71], v0 offset:2048
	ds_read_b128 v[76:79], v0 offset:4096
	ds_read_b128 v[84:87], v0 offset:6144
	ds_read_b128 v[180:183], v0 offset:8192
	ds_read_b128 v[184:187], v0 offset:10240
	ds_read_b128 v[188:191], v0 offset:12288
	ds_read_b128 v[192:195], v0 offset:14336
	v_mov_b32_e32 v0, v208
	s_waitcnt lgkmcnt(7)
	v_mfma_f32_16x16x32_bf16 v[140:143], v[56:59], v[156:159], v[140:143]
	v_and_b32_e32 v2, 15, v0
	v_lshrrev_b32_e32 v3, 1, v0
	v_mfma_f32_16x16x32_bf16 v[196:199], v[56:59], v[160:163], v[136:139]
	s_nop 2
	v_and_or_b32 v136, v3, 32, v2
	v_and_b32_e32 v2, 0xffffff80, v0
	v_lshrrev_b32_e32 v0, 2, v0
	v_and_or_b32 v2, v0, 12, v2
	v_ashrrev_i32_e32 v3, 31, v2
	v_lshl_add_u64 v[2:3], v[2:3], 1, s[6:7]
	v_lshlrev_b32_e32 v0, 13, v136
	v_mfma_f32_16x16x32_bf16 v[200:203], v[56:59], v[172:175], v[132:135]
	v_cvt_pk_bf16_f32 v138, v140, v141
	v_cvt_pk_bf16_f32 v139, v142, v143
	v_lshl_add_u64 v[136:137], v[2:3], 0, v[0:1]
	v_mfma_f32_16x16x32_bf16 v[132:135], v[56:59], v[176:179], v[128:131]
	global_store_dwordx2 v[136:137], v[138:139], off
	v_or_b32_e32 v138, 0x20000, v0
	v_mov_b32_e32 v139, v1
	s_waitcnt lgkmcnt(6)
	v_mfma_f32_16x16x32_bf16 v[128:131], v[68:71], v[156:159], v[124:127]
	v_cvt_pk_bf16_f32 v140, v196, v197
	v_cvt_pk_bf16_f32 v141, v198, v199
	v_lshl_add_u64 v[142:143], v[2:3], 0, v[138:139]
	v_mfma_f32_16x16x32_bf16 v[124:127], v[68:71], v[160:163], v[120:123]
	global_store_dwordx2 v[142:143], v[140:141], off
	v_or_b32_e32 v140, 0x80000, v0
	v_or_b32_e32 v0, 0xa0000, v0
	v_mfma_f32_16x16x32_bf16 v[120:123], v[68:71], v[172:175], v[116:119]
	v_cvt_pk_bf16_f32 v132, v132, v133
	v_cvt_pk_bf16_f32 v133, v134, v135
	v_lshl_add_u64 v[134:135], v[2:3], 0, v[0:1]
	v_mfma_f32_16x16x32_bf16 v[116:119], v[68:71], v[176:179], v[112:115]
	global_store_dwordx2 v[134:135], v[132:133], off
	v_lshl_add_u64 v[132:133], v[2:3], 0, 32
	s_mov_b64 s[6:7], 0x60
	s_waitcnt lgkmcnt(5)
	v_mfma_f32_16x16x32_bf16 v[112:115], v[76:79], v[156:159], v[108:111]
	v_mov_b32_e32 v141, v1
	s_nop 1
	v_cvt_pk_bf16_f32 v116, v116, v117
	v_cvt_pk_bf16_f32 v117, v118, v119
	v_mfma_f32_16x16x32_bf16 v[108:111], v[76:79], v[160:163], v[104:107]
	v_lshl_add_u64 v[118:119], v[132:133], 0, v[0:1]
	global_store_dwordx2 v[118:119], v[116:117], off
	v_lshl_add_u64 v[116:117], v[2:3], 0, 64
	v_mfma_f32_16x16x32_bf16 v[104:107], v[76:79], v[172:175], v[100:103]
	v_cvt_pk_bf16_f32 v142, v200, v201
	v_cvt_pk_bf16_f32 v143, v202, v203
	v_cvt_pk_bf16_f32 v128, v128, v129
	v_mfma_f32_16x16x32_bf16 v[100:103], v[76:79], v[176:179], v[96:99]
	v_cvt_pk_bf16_f32 v129, v130, v131
	v_cvt_pk_bf16_f32 v124, v124, v125
	v_cvt_pk_bf16_f32 v125, v126, v127
	s_waitcnt lgkmcnt(4)
	v_mfma_f32_16x16x32_bf16 v[96:99], v[84:87], v[156:159], v[92:95]
	v_lshl_add_u64 v[126:127], v[132:133], 0, v[138:139]
	s_nop 1
	v_cvt_pk_bf16_f32 v100, v100, v101
	v_cvt_pk_bf16_f32 v101, v102, v103
	v_mfma_f32_16x16x32_bf16 v[92:95], v[84:87], v[160:163], v[88:91]
	v_lshl_add_u64 v[102:103], v[116:117], 0, v[0:1]
	global_store_dwordx2 v[102:103], v[100:101], off
	v_lshl_add_u64 v[100:101], v[2:3], 0, s[6:7]
	v_mfma_f32_16x16x32_bf16 v[88:91], v[84:87], v[172:175], v[80:83]
	s_mov_b64 s[6:7], 0x80
	v_cvt_pk_bf16_f32 v120, v120, v121
	v_cvt_pk_bf16_f32 v121, v122, v123
	v_mfma_f32_16x16x32_bf16 v[84:87], v[84:87], v[176:179], v[72:75]
	v_lshl_add_u64 v[122:123], v[132:133], 0, v[140:141]
	v_cvt_pk_bf16_f32 v112, v112, v113
	v_cvt_pk_bf16_f32 v113, v114, v115
	s_waitcnt lgkmcnt(3)
	v_mfma_f32_16x16x32_bf16 v[68:71], v[180:183], v[176:179], v[48:51]
	v_cvt_pk_bf16_f32 v108, v108, v109
	s_nop 1
	v_cvt_pk_bf16_f32 v84, v84, v85
	v_cvt_pk_bf16_f32 v85, v86, v87
	v_mfma_f32_16x16x32_bf16 v[72:75], v[180:183], v[172:175], v[52:55]
	v_lshl_add_u64 v[86:87], v[100:101], 0, v[0:1]
	global_store_dwordx2 v[86:87], v[84:85], off
	v_lshl_add_u64 v[84:85], v[2:3], 0, s[6:7]
	s_waitcnt lgkmcnt(2)
; __device__ void even_in_tile(const P& p, int li_even, int tm, int tn, char* smem) {
;     ...
; #pragma unroll
;     for (int i = 0; i < MI; ++i)
; #pragma unroll
;       for (int j = 0; j < 4; ++j) {
;         u32x2 v;
;         v.x = pk_bf16(acc[i][j][0], acc[i][j][1]);
;         v.y = pk_bf16(acc[i][j][2], acc[i][j][3]);
;         *(u32x2*)(dst + (size_t)NCOLS(j) * 4096 + s0 + MROWS(i)) = v;
;       }
;     return;
	v_mfma_f32_16x16x32_bf16 v[52:55], v[184:187], v[176:179], v[32:35]
	v_cvt_pk_bf16_f32 v68, v68, v69
	v_cvt_pk_bf16_f32 v69, v70, v71
	v_lshl_add_u64 v[70:71], v[84:85], 0, v[0:1]
	s_mov_b64 s[6:7], 0xa0
	v_mfma_f32_16x16x32_bf16 v[80:83], v[180:183], v[156:159], v[64:67]
	global_store_dwordx2 v[70:71], v[68:69], off
	v_lshl_add_u64 v[68:69], v[2:3], 0, s[6:7]
	s_nop 0
	v_cvt_pk_bf16_f32 v52, v52, v53
	v_mfma_f32_16x16x32_bf16 v[76:79], v[180:183], v[160:163], v[60:63]
	v_cvt_pk_bf16_f32 v53, v54, v55
	v_lshl_add_u64 v[54:55], v[68:69], 0, v[0:1]
	s_mov_b64 s[6:7], 0xc0
	v_mfma_f32_16x16x32_bf16 v[64:67], v[184:187], v[156:159], v[44:47]
	global_store_dwordx2 v[54:55], v[52:53], off
	v_lshl_add_u64 v[52:53], v[2:3], 0, s[6:7]
	s_mov_b64 s[6:7], 0xe0
	v_mfma_f32_16x16x32_bf16 v[60:63], v[184:187], v[160:163], v[40:43]
	v_cvt_pk_bf16_f32 v109, v110, v111
	v_lshl_add_u64 v[110:111], v[116:117], 0, v[138:139]
	v_cvt_pk_bf16_f32 v104, v104, v105
	v_mfma_f32_16x16x32_bf16 v[56:59], v[184:187], v[172:175], v[36:39]
	v_cvt_pk_bf16_f32 v105, v106, v107
	v_lshl_add_u64 v[106:107], v[116:117], 0, v[140:141]
	v_cvt_pk_bf16_f32 v96, v96, v97
	s_waitcnt lgkmcnt(1)
	v_mfma_f32_16x16x32_bf16 v[48:51], v[188:191], v[156:159], v[28:31]
	v_cvt_pk_bf16_f32 v97, v98, v99
	v_cvt_pk_bf16_f32 v92, v92, v93
	v_cvt_pk_bf16_f32 v93, v94, v95
	v_mfma_f32_16x16x32_bf16 v[44:47], v[188:191], v[160:163], v[24:27]
	v_lshl_add_u64 v[94:95], v[100:101], 0, v[138:139]
	v_cvt_pk_bf16_f32 v88, v88, v89
	v_cvt_pk_bf16_f32 v89, v90, v91
	v_mfma_f32_16x16x32_bf16 v[40:43], v[188:191], v[172:175], v[164:167]
	v_lshl_add_u64 v[90:91], v[100:101], 0, v[140:141]
	v_cvt_pk_bf16_f32 v80, v80, v81
	v_cvt_pk_bf16_f32 v81, v82, v83
	v_mfma_f32_16x16x32_bf16 v[36:39], v[188:191], v[176:179], v[168:171]
	v_cvt_pk_bf16_f32 v76, v76, v77
	v_cvt_pk_bf16_f32 v77, v78, v79
	v_lshl_add_u64 v[78:79], v[84:85], 0, v[138:139]
	s_waitcnt lgkmcnt(0)
	v_mfma_f32_16x16x32_bf16 v[32:35], v[192:195], v[156:159], v[148:151]
	v_cvt_pk_bf16_f32 v72, v72, v73
	v_cvt_pk_bf16_f32 v73, v74, v75
	v_lshl_add_u64 v[74:75], v[84:85], 0, v[140:141]
	v_mfma_f32_16x16x32_bf16 v[28:31], v[192:195], v[160:163], v[152:155]
	v_cvt_pk_bf16_f32 v64, v64, v65
	v_cvt_pk_bf16_f32 v65, v66, v67
	v_cvt_pk_bf16_f32 v60, v60, v61
	v_mfma_f32_16x16x32_bf16 v[24:27], v[192:195], v[172:175], v[20:23]
	v_cvt_pk_bf16_f32 v61, v62, v63
	v_lshl_add_u64 v[62:63], v[68:69], 0, v[138:139]
	v_cvt_pk_bf16_f32 v56, v56, v57
	v_mfma_f32_16x16x32_bf16 v[20:23], v[192:195], v[176:179], v[144:147]
	v_cvt_pk_bf16_f32 v57, v58, v59
	v_lshl_add_u64 v[58:59], v[68:69], 0, v[140:141]
	v_cvt_pk_bf16_f32 v48, v48, v49
	v_lshl_add_u64 v[144:145], v[2:3], 0, v[140:141]
	v_lshl_add_u64 v[2:3], v[2:3], 0, s[6:7]
	v_cvt_pk_bf16_f32 v49, v50, v51
	v_cvt_pk_bf16_f32 v44, v44, v45
	v_cvt_pk_bf16_f32 v45, v46, v47
	v_lshl_add_u64 v[46:47], v[52:53], 0, v[138:139]
	v_cvt_pk_bf16_f32 v40, v40, v41
	v_cvt_pk_bf16_f32 v41, v42, v43
	v_lshl_add_u64 v[42:43], v[52:53], 0, v[140:141]
	v_cvt_pk_bf16_f32 v36, v36, v37
	v_cvt_pk_bf16_f32 v37, v38, v39
	v_lshl_add_u64 v[38:39], v[52:53], 0, v[0:1]
	v_cvt_pk_bf16_f32 v32, v32, v33
	v_cvt_pk_bf16_f32 v33, v34, v35
	v_cvt_pk_bf16_f32 v28, v28, v29
	v_cvt_pk_bf16_f32 v29, v30, v31
	v_lshl_add_u64 v[30:31], v[2:3], 0, v[138:139]
	v_cvt_pk_bf16_f32 v24, v24, v25
	v_cvt_pk_bf16_f32 v25, v26, v27
	v_lshl_add_u64 v[26:27], v[2:3], 0, v[140:141]
	v_cvt_pk_bf16_f32 v20, v20, v21
	v_cvt_pk_bf16_f32 v21, v22, v23
	v_lshl_add_u64 v[2:3], v[2:3], 0, v[0:1]
	global_store_dwordx2 v[144:145], v[142:143], off
	global_store_dwordx2 v[136:137], v[128:129], off offset:32
	global_store_dwordx2 v[126:127], v[124:125], off
	global_store_dwordx2 v[122:123], v[120:121], off
	global_store_dwordx2 v[136:137], v[112:113], off offset:64
	global_store_dwordx2 v[110:111], v[108:109], off
	global_store_dwordx2 v[106:107], v[104:105], off
	global_store_dwordx2 v[136:137], v[96:97], off offset:96
	global_store_dwordx2 v[94:95], v[92:93], off
	global_store_dwordx2 v[90:91], v[88:89], off
	global_store_dwordx2 v[136:137], v[80:81], off offset:128
	global_store_dwordx2 v[78:79], v[76:77], off
	global_store_dwordx2 v[74:75], v[72:73], off
	global_store_dwordx2 v[136:137], v[64:65], off offset:160
	global_store_dwordx2 v[62:63], v[60:61], off
	global_store_dwordx2 v[58:59], v[56:57], off
	global_store_dwordx2 v[136:137], v[48:49], off offset:192
	global_store_dwordx2 v[46:47], v[44:45], off
	global_store_dwordx2 v[42:43], v[40:41], off
	global_store_dwordx2 v[38:39], v[36:37], off
	global_store_dwordx2 v[136:137], v[32:33], off offset:224
	global_store_dwordx2 v[30:31], v[28:29], off
	global_store_dwordx2 v[26:27], v[24:25], off
	global_store_dwordx2 v[2:3], v[20:21], off
	s_branch .LBB0_294
